# sc1 also on the in-proj epilogue's Z / cache-output stores (consumed by the attention phase on other CUs), with nt streams and sc1 ACT stores
# baseline (speedup 1.0000x reference)
;     __device__ __forceinline__ void operator()(AccRef acc, const pg8::Unit& u, int wr, int wc, int, int) const {
;     ...
;                 const int row = pm * 256 + ai * 128 + wr * 64 + m * 16 + fr;
;                 const float rstd = __builtin_amdgcn_rsqf(sq[ai][m] * (1.0f / DM) + EPS) * (isq ? QSCALE : 1.0f);
;                 const int pos = samp ? 2048 + ((row - MP) & 63) : (row & 16383);
; #pragma unroll
;                 for (int bj = 0; bj < 2; ++bj) {
;                     const int c0 = pn * 256 + bj * 128 + wc * 32 + 8 * fq;
;                     float v[8];
; #pragma unroll
;                     for (int j = 0; j < 4; ++j) { v[j] = acc[ai][bj][m][0][j] * rstd; v[4 + j] = acc[ai][bj][m][1][j] * rstd; }
;                     const bool ropet = (pn == 6 || pn == 7 || (pn == 8 && bj == 0)) && ((wc & 1) == 0);
;                     if (ropet) {
;                         float pv[8];
; #pragma unroll
;                         for (int j = 0; j < 8; ++j) pv[j] = __shfl_xor(v[j], 16);
;                         if (fq < 2) {
;                             const f32x4* cs = (const f32x4*)(rope + (size_t)pos * 16);
;                             const float sg = (fq == 0) ? -1.f : 1.f;
; #pragma unroll
;                             for (int jj = 0; jj < 4; ++jj) { const f32x4 t = cs[jj];
;                                 v[2 * jj] = v[2 * jj] * t[0] + sg * pv[2 * jj] * t[1];
;                                 v[2 * jj + 1] = v[2 * jj + 1] * t[2] + sg * pv[2 * jj + 1] * t[3]; }
;                         }
;                     }
;                     v4u w; w.x = cvt_pk(v[0], v[1]); w.y = cvt_pk(v[2], v[3]); w.z = cvt_pk(v[4], v[5]); w.w = cvt_pk(v[6], v[7]);
;                     *(v4u*)(Z + (size_t)row * NIN + c0) = w;
;                     if (wrA) {
;                         const int colA = c0 - (pn < 4 ? 512 : 1024);
;                         float* dst;
;                         if (samp) { const int rs = row - MP; dst = out + (pn < 4 ? O_AKS : O_AVS) + (size_t)l * 16 * 512 * 512 + ((size_t)((rs >> 6) * 512 + 448 + (rs & 63))) * 512 + colA; }
;                         else { const int sq = (row & 16383) - 15872; dst = out + (pn < 4 ? O_AKP : O_AVP) + (size_t)l * 2 * 512 * 512 + ((size_t)((row >> 14) * 512 + sq)) * 512 + colA; }
;                         *(f32x4*)dst = (f32x4){v[0], v[1], v[2], v[3]}; *(f32x4*)(dst + 4) = (f32x4){v[4], v[5], v[6], v[7]};
.LBB0_162:
	s_add_u32 s66, s8, 0xba00000
	s_addc_u32 s67, s9, 0
	s_add_i32 s8, s12, -2
	s_cmp_lt_u32 s8, 4
	s_cselect_b64 s[8:9], -1, 0
	s_and_b32 s13, s84, 62
	s_cmp_eq_u32 s13, 62
	s_cselect_b64 s[14:15], -1, 0
	s_or_b64 s[14:15], s[4:5], s[14:15]
	s_and_b64 s[14:15], s[8:9], s[14:15]
	s_lshl_b32 s8, s12, 8
	v_readlane_b32 s9, v249, 44
	s_or_b32 s8, s8, s9
	s_waitcnt lgkmcnt(3)
	v_lshl_add_u32 v146, v145, 3, s8
	s_cmp_lt_i32 s12, 4
	s_movk_i32 s8, 0xfe00
	s_cselect_b32 s38, s8, 0xfffffc00
	s_mov_b32 s8, 0x8400000
	s_cselect_b32 s8, s8, 0x8800000
	s_mov_b32 s9, 0x8c80000
	s_cselect_b32 s9, s9, 0xac80000
	s_add_u32 s42, s94, s8
	s_addc_u32 s43, s95, 0
	s_add_u32 s30, s94, s9
	s_addc_u32 s31, s95, 0
	s_ashr_i32 s8, s53, 5
	s_and_b32 s36, s8, 0xfffffe00
	s_addk_i32 s36, 0xc200
	v_mov_b64_e32 v[148:149], s[66:67]
	v_mad_i64_i32 v[144:145], s[8:9], v144, s71, v[148:149]
	v_add_u32_e32 v148, s36, v157
	s_lshl_b32 s87, s53, 3
	v_ashrrev_i32_e32 v149, 31, v148
	s_add_i32 s87, s87, 0xfffc01c0
	v_lshlrev_b64 v[148:149], 11, v[148:149]
	v_lshl_add_u64 v[160:161], s[42:43], 0, v[148:149]
	v_or_b32_e32 v148, s87, v177
	v_ashrrev_i32_e32 v149, 31, v148
	v_lshlrev_b64 v[148:149], 11, v[148:149]
	v_lshl_add_u64 v[164:165], s[30:31], 0, v[148:149]
	s_waitcnt lgkmcnt(2)
	v_ashrrev_i32_e32 v147, 31, v146
	s_waitcnt lgkmcnt(0)
	v_cndmask_b32_e64 v136, 0, 1, s[14:15]
	v_add_u32_e32 v148, s38, v146
	v_lshl_add_u64 v[162:163], v[146:147], 1, v[144:145]
	v_cmp_ne_u32_e64 s[8:9], 1, v136
	s_andn2_b64 vcc, exec, s[14:15]
	v_cndmask_b32_e64 v161, v161, v165, s[4:5]
	v_cndmask_b32_e64 v160, v160, v164, s[4:5]
	v_ashrrev_i32_e32 v149, 31, v148
	v_cvt_pk_bf16_f32 v184, v124, v125
	v_cvt_pk_bf16_f32 v185, v126, v127
	v_cvt_pk_bf16_f32 v186, v120, v121
	v_cvt_pk_bf16_f32 v187, v122, v123
	global_store_dwordx4 v[162:163], v[184:187], off sc1
	s_cbranch_vccnz .LBB0_164
	v_lshl_add_u64 v[144:145], v[148:149], 2, v[160:161]
	global_store_dwordx4 v[144:145], v[124:127], off sc1
	global_store_dwordx4 v[144:145], v[120:123], off offset:16 sc1
.LBB0_164:
	s_cmp_eq_u32 s12, 8
	s_cselect_b64 s[54:55], -1, 0
	s_lshl_b32 s37, s53, 1
	s_add_i32 s37, s37, 0xffff0040
	v_or_b32_e32 v144, s37, v177
	v_ashrrev_i32_e32 v145, 31, v144
	v_lshlrev_b64 v[144:145], 9, v[144:145]
	s_and_b64 s[12:13], s[54:55], s[4:5]
	v_cndmask_b32_e64 v136, 0, 1, s[12:13]
	v_lshl_add_u64 v[164:165], s[94:95], 0, v[144:145]
	v_add_u32_e32 v144, 0xfffff800, v146
	v_cmp_ne_u32_e64 s[14:15], 1, v136
	s_andn2_b64 vcc, exec, s[12:13]
	v_ashrrev_i32_e32 v145, 31, v144
	s_cbranch_vccnz .LBB0_166
	v_lshl_add_u64 v[184:185], v[144:145], 2, v[164:165]
	v_lshl_add_u64 v[186:187], v[184:185], 0, s[80:81]
	v_add_co_u32_e32 v184, vcc, 0xcc80000, v184
	s_nop 1
	v_addc_co_u32_e32 v185, vcc, 0, v185, vcc
	global_store_dwordx4 v[184:185], v[124:127], off sc1
	global_store_dwordx4 v[186:187], v[120:123], off offset:16 sc1

; __device__ __forceinline__ unsigned cvt_pk(float lo, float hi) { unsigned r; asm("v_cvt_pk_bf16_f32 %0, %1, %2" : "=v"(r) : "v"(lo), "v"(hi)); return r; }
;     __device__ __forceinline__ void operator()(AccRef acc, const pg8::Unit& u, int wr, int wc, int, int) const {
;     ...
;                     v4u w; w.x = cvt_pk(v[0], v[1]); w.y = cvt_pk(v[2], v[3]); w.z = cvt_pk(v[4], v[5]); w.w = cvt_pk(v[6], v[7]);
;                     *(v4u*)(Z + (size_t)row * NIN + c0) = w;
;                     if (wrA) {
;                         const int colA = c0 - (pn < 4 ? 512 : 1024);
;                         float* dst;
;                         if (samp) { const int rs = row - MP; dst = out + (pn < 4 ? O_AKS : O_AVS) + (size_t)l * 16 * 512 * 512 + ((size_t)((rs >> 6) * 512 + 448 + (rs & 63))) * 512 + colA; }
;                         else { const int sq = (row & 16383) - 15872; dst = out + (pn < 4 ? O_AKP : O_AVP) + (size_t)l * 2 * 512 * 512 + ((size_t)((row >> 14) * 512 + sq)) * 512 + colA; }
;                         *(f32x4*)dst = (f32x4){v[0], v[1], v[2], v[3]}; *(f32x4*)(dst + 4) = (f32x4){v[4], v[5], v[6], v[7]};
;                     }
;                     if (wrB && (samp || ai == 1)) {
;                         const int colB = c0 - (bj == 0 ? 2048 : 2176);
;                         float* dst;
;                         if (samp) { const int rs = row - MP; dst = out + (bj == 0 ? O_BKS : O_BVS) + (size_t)l * 16 * 128 * 128 + ((size_t)((rs >> 6) * 128 + 64 + (rs & 63))) * 128 + colB; }
;                         else { const int sq = (row & 16383) - 16256; dst = out + (bj == 0 ? O_BKP : O_BVP) + (size_t)l * 2 * 128 * 128 + ((size_t)((row >> 14) * 128 + sq)) * 128 + colB; }
;                         *(f32x4*)dst = (f32x4){v[0], v[1], v[2], v[3]}; *(f32x4*)(dst + 4) = (f32x4){v[4], v[5], v[6], v[7]};
;                     }
.LBB0_170:
	s_waitcnt lgkmcnt(7)
	v_add_u32_e32 v124, 0x80, v146
	s_waitcnt lgkmcnt(3)
	v_cvt_pk_bf16_f32 v120, v116, v117
	s_waitcnt lgkmcnt(2)
	v_cvt_pk_bf16_f32 v121, v118, v119
	v_cvt_pk_bf16_f32 v122, v112, v113
	v_cvt_pk_bf16_f32 v123, v114, v115
	global_store_dwordx4 v[162:163], v[120:123], off offset:256 sc1
	s_and_b64 vcc, exec, s[8:9]
	s_nop 0
	v_add_u32_e32 v120, s38, v124
	v_ashrrev_i32_e32 v121, 31, v120
	s_cbranch_vccnz .LBB0_172
	v_lshl_add_u64 v[122:123], v[120:121], 2, v[160:161]
	global_store_dwordx4 v[122:123], v[116:119], off sc1
	global_store_dwordx4 v[122:123], v[112:115], off offset:16 sc1
.LBB0_172:
	s_and_b64 vcc, exec, s[14:15]
	s_cbranch_vccnz .LBB0_174
	v_lshl_add_u64 v[122:123], v[144:145], 2, v[164:165]
	v_lshl_add_u64 v[124:125], v[122:123], 0, s[82:83]
	v_add_co_u32_e32 v122, vcc, 0xce80000, v122
	s_nop 1
	v_addc_co_u32_e32 v123, vcc, 0, v123, vcc
	global_store_dwordx4 v[122:123], v[116:119], off sc1
	global_store_dwordx4 v[124:125], v[112:115], off offset:16 sc1

;     __device__ __forceinline__ void operator()(AccRef acc, const pg8::Unit& u, int wr, int wc, int, int) const {
;     ...
;                 const int row = pm * 256 + ai * 128 + wr * 64 + m * 16 + fr;
;                 const float rstd = __builtin_amdgcn_rsqf(sq[ai][m] * (1.0f / DM) + EPS) * (isq ? QSCALE : 1.0f);
;                 const int pos = samp ? 2048 + ((row - MP) & 63) : (row & 16383);
; #pragma unroll
;                 for (int bj = 0; bj < 2; ++bj) {
;                     const int c0 = pn * 256 + bj * 128 + wc * 32 + 8 * fq;
;                     float v[8];
; #pragma unroll
;                     for (int j = 0; j < 4; ++j) { v[j] = acc[ai][bj][m][0][j] * rstd; v[4 + j] = acc[ai][bj][m][1][j] * rstd; }
;                     const bool ropet = (pn == 6 || pn == 7 || (pn == 8 && bj == 0)) && ((wc & 1) == 0);
;                     if (ropet) {
;                         float pv[8];
; #pragma unroll
;                         for (int j = 0; j < 8; ++j) pv[j] = __shfl_xor(v[j], 16);
;                         if (fq < 2) {
;                             const f32x4* cs = (const f32x4*)(rope + (size_t)pos * 16);
;                             const float sg = (fq == 0) ? -1.f : 1.f;
; #pragma unroll
;                             for (int jj = 0; jj < 4; ++jj) { const f32x4 t = cs[jj];
;                                 v[2 * jj] = v[2 * jj] * t[0] + sg * pv[2 * jj] * t[1];
;                                 v[2 * jj + 1] = v[2 * jj + 1] * t[2] + sg * pv[2 * jj + 1] * t[3]; }
;                         }
;                     }
;                     v4u w; w.x = cvt_pk(v[0], v[1]); w.y = cvt_pk(v[2], v[3]); w.z = cvt_pk(v[4], v[5]); w.w = cvt_pk(v[6], v[7]);
;                     *(v4u*)(Z + (size_t)row * NIN + c0) = w;
;                     if (wrA) {
;                         const int colA = c0 - (pn < 4 ? 512 : 1024);
;                         float* dst;
;                         if (samp) { const int rs = row - MP; dst = out + (pn < 4 ? O_AKS : O_AVS) + (size_t)l * 16 * 512 * 512 + ((size_t)((rs >> 6) * 512 + 448 + (rs & 63))) * 512 + colA; }
;                         else { const int sq = (row & 16383) - 15872; dst = out + (pn < 4 ? O_AKP : O_AVP) + (size_t)l * 2 * 512 * 512 + ((size_t)((row >> 14) * 512 + sq)) * 512 + colA; }
;                         *(f32x4*)dst = (f32x4){v[0], v[1], v[2], v[3]}; *(f32x4*)(dst + 4) = (f32x4){v[4], v[5], v[6], v[7]};
.LBB0_178:
	s_waitcnt lgkmcnt(5)
	v_add_u32_e32 v118, s36, v115
	s_waitcnt lgkmcnt(4)
	v_ashrrev_i32_e32 v119, 31, v118
	s_waitcnt lgkmcnt(0)
	v_or_b32_e32 v124, 16, v177
	v_lshlrev_b64 v[118:119], 11, v[118:119]
	v_lshl_add_u64 v[122:123], s[42:43], 0, v[118:119]
	v_or_b32_e32 v118, s87, v124
	v_ashrrev_i32_e32 v119, 31, v118
	v_mov_b64_e32 v[116:117], s[66:67]
	v_lshlrev_b64 v[118:119], 11, v[118:119]
	v_mad_i64_i32 v[116:117], s[38:39], v154, s71, v[116:117]
	v_lshl_add_u64 v[126:127], s[30:31], 0, v[118:119]
	v_lshl_add_u64 v[118:119], v[146:147], 1, v[116:117]
	s_and_b64 vcc, exec, s[8:9]
	v_cndmask_b32_e64 v117, v123, v127, s[4:5]
	v_cndmask_b32_e64 v116, v122, v126, s[4:5]
	v_cvt_pk_bf16_f32 v156, v108, v109
	v_cvt_pk_bf16_f32 v157, v110, v111
	v_cvt_pk_bf16_f32 v158, v104, v105
	v_cvt_pk_bf16_f32 v159, v106, v107
	global_store_dwordx4 v[118:119], v[156:159], off sc1
	s_cbranch_vccnz .LBB0_180
	v_lshl_add_u64 v[122:123], v[148:149], 2, v[116:117]
	global_store_dwordx4 v[122:123], v[108:111], off sc1
	global_store_dwordx4 v[122:123], v[104:107], off offset:16 sc1
.LBB0_180:
	v_or_b32_e32 v122, s37, v124
	v_ashrrev_i32_e32 v123, 31, v122
	v_lshlrev_b64 v[122:123], 9, v[122:123]
	s_and_b64 vcc, exec, s[14:15]
	v_lshl_add_u64 v[122:123], s[94:95], 0, v[122:123]
	s_cbranch_vccnz .LBB0_182
	v_lshl_add_u64 v[126:127], v[144:145], 2, v[122:123]
	v_lshl_add_u64 v[156:157], v[126:127], 0, s[80:81]
	v_add_co_u32_e32 v126, vcc, 0xcc80000, v126
	s_nop 1
	v_addc_co_u32_e32 v127, vcc, 0, v127, vcc
	global_store_dwordx4 v[126:127], v[108:111], off sc1
	global_store_dwordx4 v[156:157], v[104:107], off offset:16 sc1

; __device__ __forceinline__ unsigned cvt_pk(float lo, float hi) { unsigned r; asm("v_cvt_pk_bf16_f32 %0, %1, %2" : "=v"(r) : "v"(lo), "v"(hi)); return r; }
;     __device__ __forceinline__ void operator()(AccRef acc, const pg8::Unit& u, int wr, int wc, int, int) const {
;     ...
;                     v4u w; w.x = cvt_pk(v[0], v[1]); w.y = cvt_pk(v[2], v[3]); w.z = cvt_pk(v[4], v[5]); w.w = cvt_pk(v[6], v[7]);
;                     *(v4u*)(Z + (size_t)row * NIN + c0) = w;
;                     if (wrA) {
;                         const int colA = c0 - (pn < 4 ? 512 : 1024);
;                         float* dst;
;                         if (samp) { const int rs = row - MP; dst = out + (pn < 4 ? O_AKS : O_AVS) + (size_t)l * 16 * 512 * 512 + ((size_t)((rs >> 6) * 512 + 448 + (rs & 63))) * 512 + colA; }
;                         else { const int sq = (row & 16383) - 15872; dst = out + (pn < 4 ? O_AKP : O_AVP) + (size_t)l * 2 * 512 * 512 + ((size_t)((row >> 14) * 512 + sq)) * 512 + colA; }
;                         *(f32x4*)dst = (f32x4){v[0], v[1], v[2], v[3]}; *(f32x4*)(dst + 4) = (f32x4){v[4], v[5], v[6], v[7]};
;                     }
;                     if (wrB && (samp || ai == 1)) {
;                         const int colB = c0 - (bj == 0 ? 2048 : 2176);
;                         float* dst;
;                         if (samp) { const int rs = row - MP; dst = out + (bj == 0 ? O_BKS : O_BVS) + (size_t)l * 16 * 128 * 128 + ((size_t)((rs >> 6) * 128 + 64 + (rs & 63))) * 128 + colB; }
;                         else { const int sq = (row & 16383) - 16256; dst = out + (bj == 0 ? O_BKP : O_BVP) + (size_t)l * 2 * 128 * 128 + ((size_t)((row >> 14) * 128 + sq)) * 128 + colB; }
;                         *(f32x4*)dst = (f32x4){v[0], v[1], v[2], v[3]}; *(f32x4*)(dst + 4) = (f32x4){v[4], v[5], v[6], v[7]};
;                     }
.LBB0_186:
	s_and_b64 vcc, exec, s[8:9]
	s_waitcnt lgkmcnt(3)
	v_cvt_pk_bf16_f32 v104, v100, v101
	s_waitcnt lgkmcnt(2)
	v_cvt_pk_bf16_f32 v105, v102, v103
	v_cvt_pk_bf16_f32 v106, v96, v97
	v_cvt_pk_bf16_f32 v107, v98, v99
	global_store_dwordx4 v[118:119], v[104:107], off offset:256 sc1
	s_cbranch_vccnz .LBB0_188
	s_nop 0
	v_lshl_add_u64 v[104:105], v[120:121], 2, v[116:117]
	global_store_dwordx4 v[104:105], v[100:103], off sc1
	global_store_dwordx4 v[104:105], v[96:99], off offset:16 sc1
.LBB0_188:
	s_and_b64 vcc, exec, s[14:15]
	s_cbranch_vccnz .LBB0_190
	v_lshl_add_u64 v[104:105], v[144:145], 2, v[122:123]
	v_lshl_add_u64 v[106:107], v[104:105], 0, s[82:83]
	v_add_co_u32_e32 v104, vcc, 0xce80000, v104
	s_nop 1
	v_addc_co_u32_e32 v105, vcc, 0, v105, vcc
	global_store_dwordx4 v[104:105], v[100:103], off sc1
	global_store_dwordx4 v[106:107], v[96:99], off offset:16 sc1

;     __device__ __forceinline__ void operator()(AccRef acc, const pg8::Unit& u, int wr, int wc, int, int) const {
;     ...
;                 const int row = pm * 256 + ai * 128 + wr * 64 + m * 16 + fr;
;                 const float rstd = __builtin_amdgcn_rsqf(sq[ai][m] * (1.0f / DM) + EPS) * (isq ? QSCALE : 1.0f);
;                 const int pos = samp ? 2048 + ((row - MP) & 63) : (row & 16383);
; #pragma unroll
;                 for (int bj = 0; bj < 2; ++bj) {
;                     const int c0 = pn * 256 + bj * 128 + wc * 32 + 8 * fq;
;                     float v[8];
; #pragma unroll
;                     for (int j = 0; j < 4; ++j) { v[j] = acc[ai][bj][m][0][j] * rstd; v[4 + j] = acc[ai][bj][m][1][j] * rstd; }
;                     const bool ropet = (pn == 6 || pn == 7 || (pn == 8 && bj == 0)) && ((wc & 1) == 0);
;                     if (ropet) {
;                         float pv[8];
; #pragma unroll
;                         for (int j = 0; j < 8; ++j) pv[j] = __shfl_xor(v[j], 16);
;                         if (fq < 2) {
;                             const f32x4* cs = (const f32x4*)(rope + (size_t)pos * 16);
;                             const float sg = (fq == 0) ? -1.f : 1.f;
; #pragma unroll
;                             for (int jj = 0; jj < 4; ++jj) { const f32x4 t = cs[jj];
;                                 v[2 * jj] = v[2 * jj] * t[0] + sg * pv[2 * jj] * t[1];
;                                 v[2 * jj + 1] = v[2 * jj + 1] * t[2] + sg * pv[2 * jj + 1] * t[3]; }
;                         }
;                     }
;                     v4u w; w.x = cvt_pk(v[0], v[1]); w.y = cvt_pk(v[2], v[3]); w.z = cvt_pk(v[4], v[5]); w.w = cvt_pk(v[6], v[7]);
;                     *(v4u*)(Z + (size_t)row * NIN + c0) = w;
;                     if (wrA) {
;                         const int colA = c0 - (pn < 4 ? 512 : 1024);
;                         float* dst;
;                         if (samp) { const int rs = row - MP; dst = out + (pn < 4 ? O_AKS : O_AVS) + (size_t)l * 16 * 512 * 512 + ((size_t)((rs >> 6) * 512 + 448 + (rs & 63))) * 512 + colA; }
;                         else { const int sq = (row & 16383) - 15872; dst = out + (pn < 4 ? O_AKP : O_AVP) + (size_t)l * 2 * 512 * 512 + ((size_t)((row >> 14) * 512 + sq)) * 512 + colA; }
;                         *(f32x4*)dst = (f32x4){v[0], v[1], v[2], v[3]}; *(f32x4*)(dst + 4) = (f32x4){v[4], v[5], v[6], v[7]};
.LBB0_194:
	s_waitcnt lgkmcnt(5)
	v_add_u32_e32 v102, s36, v99
	s_waitcnt lgkmcnt(4)
	v_ashrrev_i32_e32 v103, 31, v102
	s_waitcnt lgkmcnt(0)
	v_or_b32_e32 v106, 32, v177
	v_lshlrev_b64 v[102:103], 11, v[102:103]
	v_lshl_add_u64 v[104:105], s[42:43], 0, v[102:103]
	v_or_b32_e32 v102, s87, v106
	v_ashrrev_i32_e32 v103, 31, v102
	v_mov_b64_e32 v[100:101], s[66:67]
	v_lshlrev_b64 v[102:103], 11, v[102:103]
	v_mad_i64_i32 v[100:101], s[38:39], v152, s71, v[100:101]
	v_lshl_add_u64 v[112:113], s[30:31], 0, v[102:103]
	v_lshl_add_u64 v[102:103], v[146:147], 1, v[100:101]
	s_and_b64 vcc, exec, s[8:9]
	v_cndmask_b32_e64 v101, v105, v113, s[4:5]
	v_cndmask_b32_e64 v100, v104, v112, s[4:5]
	v_cvt_pk_bf16_f32 v108, v92, v93
	v_cvt_pk_bf16_f32 v109, v94, v95
	v_cvt_pk_bf16_f32 v110, v88, v89
	v_cvt_pk_bf16_f32 v111, v90, v91
	global_store_dwordx4 v[102:103], v[108:111], off sc1
	s_cbranch_vccnz .LBB0_196
	v_lshl_add_u64 v[104:105], v[148:149], 2, v[100:101]
	global_store_dwordx4 v[104:105], v[92:95], off sc1
	global_store_dwordx4 v[104:105], v[88:91], off offset:16 sc1
.LBB0_196:
	v_or_b32_e32 v104, s37, v106
	v_ashrrev_i32_e32 v105, 31, v104
	v_lshlrev_b64 v[104:105], 9, v[104:105]
	s_and_b64 vcc, exec, s[14:15]
	v_lshl_add_u64 v[104:105], s[94:95], 0, v[104:105]
	s_cbranch_vccnz .LBB0_198
	v_lshl_add_u64 v[108:109], v[144:145], 2, v[104:105]
	v_lshl_add_u64 v[110:111], v[108:109], 0, s[80:81]
	v_add_co_u32_e32 v108, vcc, 0xcc80000, v108
	s_nop 1
	v_addc_co_u32_e32 v109, vcc, 0, v109, vcc
	global_store_dwordx4 v[108:109], v[92:95], off sc1
	global_store_dwordx4 v[110:111], v[88:91], off offset:16 sc1

; __device__ __forceinline__ unsigned cvt_pk(float lo, float hi) { unsigned r; asm("v_cvt_pk_bf16_f32 %0, %1, %2" : "=v"(r) : "v"(lo), "v"(hi)); return r; }
;     __device__ __forceinline__ void operator()(AccRef acc, const pg8::Unit& u, int wr, int wc, int, int) const {
;     ...
;                     v4u w; w.x = cvt_pk(v[0], v[1]); w.y = cvt_pk(v[2], v[3]); w.z = cvt_pk(v[4], v[5]); w.w = cvt_pk(v[6], v[7]);
;                     *(v4u*)(Z + (size_t)row * NIN + c0) = w;
;                     if (wrA) {
;                         const int colA = c0 - (pn < 4 ? 512 : 1024);
;                         float* dst;
;                         if (samp) { const int rs = row - MP; dst = out + (pn < 4 ? O_AKS : O_AVS) + (size_t)l * 16 * 512 * 512 + ((size_t)((rs >> 6) * 512 + 448 + (rs & 63))) * 512 + colA; }
;                         else { const int sq = (row & 16383) - 15872; dst = out + (pn < 4 ? O_AKP : O_AVP) + (size_t)l * 2 * 512 * 512 + ((size_t)((row >> 14) * 512 + sq)) * 512 + colA; }
;                         *(f32x4*)dst = (f32x4){v[0], v[1], v[2], v[3]}; *(f32x4*)(dst + 4) = (f32x4){v[4], v[5], v[6], v[7]};
;                     }
;                     if (wrB && (samp || ai == 1)) {
;                         const int colB = c0 - (bj == 0 ? 2048 : 2176);
;                         float* dst;
;                         if (samp) { const int rs = row - MP; dst = out + (bj == 0 ? O_BKS : O_BVS) + (size_t)l * 16 * 128 * 128 + ((size_t)((rs >> 6) * 128 + 64 + (rs & 63))) * 128 + colB; }
;                         else { const int sq = (row & 16383) - 16256; dst = out + (bj == 0 ? O_BKP : O_BVP) + (size_t)l * 2 * 128 * 128 + ((size_t)((row >> 14) * 128 + sq)) * 128 + colB; }
;                         *(f32x4*)dst = (f32x4){v[0], v[1], v[2], v[3]}; *(f32x4*)(dst + 4) = (f32x4){v[4], v[5], v[6], v[7]};
;                     }
.LBB0_202:
	s_and_b64 vcc, exec, s[8:9]
	s_waitcnt lgkmcnt(3)
	v_cvt_pk_bf16_f32 v88, v84, v85
	s_waitcnt lgkmcnt(2)
	v_cvt_pk_bf16_f32 v89, v86, v87
	v_cvt_pk_bf16_f32 v90, v80, v81
	v_cvt_pk_bf16_f32 v91, v82, v83
	global_store_dwordx4 v[102:103], v[88:91], off offset:256 sc1
	s_cbranch_vccnz .LBB0_204
	s_nop 0
	v_lshl_add_u64 v[88:89], v[120:121], 2, v[100:101]
	global_store_dwordx4 v[88:89], v[84:87], off sc1
	global_store_dwordx4 v[88:89], v[80:83], off offset:16 sc1
.LBB0_204:
	s_and_b64 vcc, exec, s[14:15]
	s_cbranch_vccnz .LBB0_206
	v_lshl_add_u64 v[88:89], v[144:145], 2, v[104:105]
	v_lshl_add_u64 v[90:91], v[88:89], 0, s[82:83]
	v_add_co_u32_e32 v88, vcc, 0xce80000, v88
	s_nop 1
	v_addc_co_u32_e32 v89, vcc, 0, v89, vcc
	global_store_dwordx4 v[88:89], v[84:87], off sc1
	global_store_dwordx4 v[90:91], v[80:83], off offset:16 sc1

;     __device__ __forceinline__ void operator()(AccRef acc, const pg8::Unit& u, int wr, int wc, int, int) const {
;     ...
;                 const int row = pm * 256 + ai * 128 + wr * 64 + m * 16 + fr;
;                 const float rstd = __builtin_amdgcn_rsqf(sq[ai][m] * (1.0f / DM) + EPS) * (isq ? QSCALE : 1.0f);
;                 const int pos = samp ? 2048 + ((row - MP) & 63) : (row & 16383);
; #pragma unroll
;                 for (int bj = 0; bj < 2; ++bj) {
;                     const int c0 = pn * 256 + bj * 128 + wc * 32 + 8 * fq;
;                     float v[8];
; #pragma unroll
;                     for (int j = 0; j < 4; ++j) { v[j] = acc[ai][bj][m][0][j] * rstd; v[4 + j] = acc[ai][bj][m][1][j] * rstd; }
;                     const bool ropet = (pn == 6 || pn == 7 || (pn == 8 && bj == 0)) && ((wc & 1) == 0);
;                     if (ropet) {
;                         float pv[8];
; #pragma unroll
;                         for (int j = 0; j < 8; ++j) pv[j] = __shfl_xor(v[j], 16);
;                         if (fq < 2) {
;                             const f32x4* cs = (const f32x4*)(rope + (size_t)pos * 16);
;                             const float sg = (fq == 0) ? -1.f : 1.f;
; #pragma unroll
;                             for (int jj = 0; jj < 4; ++jj) { const f32x4 t = cs[jj];
;                                 v[2 * jj] = v[2 * jj] * t[0] + sg * pv[2 * jj] * t[1];
;                                 v[2 * jj + 1] = v[2 * jj + 1] * t[2] + sg * pv[2 * jj + 1] * t[3]; }
;                         }
;                     }
;                     v4u w; w.x = cvt_pk(v[0], v[1]); w.y = cvt_pk(v[2], v[3]); w.z = cvt_pk(v[4], v[5]); w.w = cvt_pk(v[6], v[7]);
;                     *(v4u*)(Z + (size_t)row * NIN + c0) = w;
;                     if (wrA) {
;                         const int colA = c0 - (pn < 4 ? 512 : 1024);
;                         float* dst;
;                         if (samp) { const int rs = row - MP; dst = out + (pn < 4 ? O_AKS : O_AVS) + (size_t)l * 16 * 512 * 512 + ((size_t)((rs >> 6) * 512 + 448 + (rs & 63))) * 512 + colA; }
;                         else { const int sq = (row & 16383) - 15872; dst = out + (pn < 4 ? O_AKP : O_AVP) + (size_t)l * 2 * 512 * 512 + ((size_t)((row >> 14) * 512 + sq)) * 512 + colA; }
;                         *(f32x4*)dst = (f32x4){v[0], v[1], v[2], v[3]}; *(f32x4*)(dst + 4) = (f32x4){v[4], v[5], v[6], v[7]};
.LBB0_210:
	s_waitcnt lgkmcnt(5)
	v_add_u32_e32 v86, s36, v83
	s_waitcnt lgkmcnt(4)
	v_ashrrev_i32_e32 v87, 31, v86
	s_waitcnt lgkmcnt(0)
	v_or_b32_e32 v90, 48, v177
	v_lshlrev_b64 v[86:87], 11, v[86:87]
	v_lshl_add_u64 v[88:89], s[42:43], 0, v[86:87]
	v_or_b32_e32 v86, s87, v90
	v_ashrrev_i32_e32 v87, 31, v86
	v_mov_b64_e32 v[84:85], s[66:67]
	v_lshlrev_b64 v[86:87], 11, v[86:87]
	v_mad_i64_i32 v[84:85], s[38:39], v150, s71, v[84:85]
	v_lshl_add_u64 v[96:97], s[30:31], 0, v[86:87]
	v_lshl_add_u64 v[86:87], v[146:147], 1, v[84:85]
	s_and_b64 vcc, exec, s[8:9]
	v_cndmask_b32_e64 v85, v89, v97, s[4:5]
	v_cndmask_b32_e64 v84, v88, v96, s[4:5]
	v_cvt_pk_bf16_f32 v92, v76, v77
	v_cvt_pk_bf16_f32 v93, v78, v79
	v_cvt_pk_bf16_f32 v94, v72, v73
	v_cvt_pk_bf16_f32 v95, v74, v75
	global_store_dwordx4 v[86:87], v[92:95], off sc1
	s_cbranch_vccnz .LBB0_212
	v_lshl_add_u64 v[88:89], v[148:149], 2, v[84:85]
	global_store_dwordx4 v[88:89], v[76:79], off sc1
	global_store_dwordx4 v[88:89], v[72:75], off offset:16 sc1
.LBB0_212:
	v_or_b32_e32 v88, s37, v90
	v_ashrrev_i32_e32 v89, 31, v88
	v_lshlrev_b64 v[88:89], 9, v[88:89]
	s_and_b64 vcc, exec, s[14:15]
	v_lshl_add_u64 v[88:89], s[94:95], 0, v[88:89]
	s_cbranch_vccnz .LBB0_214
	v_lshl_add_u64 v[92:93], v[144:145], 2, v[88:89]
	v_lshl_add_u64 v[94:95], v[92:93], 0, s[80:81]
	v_add_co_u32_e32 v92, vcc, 0xcc80000, v92
	s_nop 1
	v_addc_co_u32_e32 v93, vcc, 0, v93, vcc
	global_store_dwordx4 v[92:93], v[76:79], off sc1
	global_store_dwordx4 v[94:95], v[72:75], off offset:16 sc1

; __device__ __forceinline__ unsigned cvt_pk(float lo, float hi) { unsigned r; asm("v_cvt_pk_bf16_f32 %0, %1, %2" : "=v"(r) : "v"(lo), "v"(hi)); return r; }
;     __device__ __forceinline__ void operator()(AccRef acc, const pg8::Unit& u, int wr, int wc, int, int) const {
;     ...
;                     v4u w; w.x = cvt_pk(v[0], v[1]); w.y = cvt_pk(v[2], v[3]); w.z = cvt_pk(v[4], v[5]); w.w = cvt_pk(v[6], v[7]);
;                     *(v4u*)(Z + (size_t)row * NIN + c0) = w;
;                     if (wrA) {
;                         const int colA = c0 - (pn < 4 ? 512 : 1024);
;                         float* dst;
;                         if (samp) { const int rs = row - MP; dst = out + (pn < 4 ? O_AKS : O_AVS) + (size_t)l * 16 * 512 * 512 + ((size_t)((rs >> 6) * 512 + 448 + (rs & 63))) * 512 + colA; }
;                         else { const int sq = (row & 16383) - 15872; dst = out + (pn < 4 ? O_AKP : O_AVP) + (size_t)l * 2 * 512 * 512 + ((size_t)((row >> 14) * 512 + sq)) * 512 + colA; }
;                         *(f32x4*)dst = (f32x4){v[0], v[1], v[2], v[3]}; *(f32x4*)(dst + 4) = (f32x4){v[4], v[5], v[6], v[7]};
;                     }
;                     if (wrB && (samp || ai == 1)) {
;                         const int colB = c0 - (bj == 0 ? 2048 : 2176);
;                         float* dst;
;                         if (samp) { const int rs = row - MP; dst = out + (bj == 0 ? O_BKS : O_BVS) + (size_t)l * 16 * 128 * 128 + ((size_t)((rs >> 6) * 128 + 64 + (rs & 63))) * 128 + colB; }
;                         else { const int sq = (row & 16383) - 16256; dst = out + (bj == 0 ? O_BKP : O_BVP) + (size_t)l * 2 * 128 * 128 + ((size_t)((row >> 14) * 128 + sq)) * 128 + colB; }
;                         *(f32x4*)dst = (f32x4){v[0], v[1], v[2], v[3]}; *(f32x4*)(dst + 4) = (f32x4){v[4], v[5], v[6], v[7]};
;                     }
.LBB0_218:
	s_and_b64 vcc, exec, s[8:9]
	s_waitcnt lgkmcnt(3)
	v_cvt_pk_bf16_f32 v72, v68, v69
	s_waitcnt lgkmcnt(2)
	v_cvt_pk_bf16_f32 v73, v70, v71
	v_cvt_pk_bf16_f32 v74, v64, v65
	v_cvt_pk_bf16_f32 v75, v66, v67
	global_store_dwordx4 v[86:87], v[72:75], off offset:256 sc1
	s_cbranch_vccnz .LBB0_220
	s_nop 0
	v_lshl_add_u64 v[72:73], v[120:121], 2, v[84:85]
	global_store_dwordx4 v[72:73], v[68:71], off sc1
	global_store_dwordx4 v[72:73], v[64:67], off offset:16 sc1
.LBB0_220:
	s_and_b64 vcc, exec, s[14:15]
	s_cbranch_vccnz .LBB0_222
	v_lshl_add_u64 v[72:73], v[144:145], 2, v[88:89]
	v_lshl_add_u64 v[74:75], v[72:73], 0, s[82:83]
	v_add_co_u32_e32 v72, vcc, 0xce80000, v72
	s_nop 1
	v_addc_co_u32_e32 v73, vcc, 0, v73, vcc
	global_store_dwordx4 v[72:73], v[68:71], off sc1
	global_store_dwordx4 v[74:75], v[64:67], off offset:16 sc1

;     __device__ __forceinline__ void operator()(AccRef acc, const pg8::Unit& u, int wr, int wc, int, int) const {
;     ...
;                 const int row = pm * 256 + ai * 128 + wr * 64 + m * 16 + fr;
;                 const float rstd = __builtin_amdgcn_rsqf(sq[ai][m] * (1.0f / DM) + EPS) * (isq ? QSCALE : 1.0f);
;                 const int pos = samp ? 2048 + ((row - MP) & 63) : (row & 16383);
; #pragma unroll
;                 for (int bj = 0; bj < 2; ++bj) {
;                     const int c0 = pn * 256 + bj * 128 + wc * 32 + 8 * fq;
;                     float v[8];
; #pragma unroll
;                     for (int j = 0; j < 4; ++j) { v[j] = acc[ai][bj][m][0][j] * rstd; v[4 + j] = acc[ai][bj][m][1][j] * rstd; }
;                     const bool ropet = (pn == 6 || pn == 7 || (pn == 8 && bj == 0)) && ((wc & 1) == 0);
;                     if (ropet) {
;                         float pv[8];
; #pragma unroll
;                         for (int j = 0; j < 8; ++j) pv[j] = __shfl_xor(v[j], 16);
;                         if (fq < 2) {
;                             const f32x4* cs = (const f32x4*)(rope + (size_t)pos * 16);
;                             const float sg = (fq == 0) ? -1.f : 1.f;
; #pragma unroll
;                             for (int jj = 0; jj < 4; ++jj) { const f32x4 t = cs[jj];
;                                 v[2 * jj] = v[2 * jj] * t[0] + sg * pv[2 * jj] * t[1];
;                                 v[2 * jj + 1] = v[2 * jj + 1] * t[2] + sg * pv[2 * jj + 1] * t[3]; }
;                         }
;                     }
;                     v4u w; w.x = cvt_pk(v[0], v[1]); w.y = cvt_pk(v[2], v[3]); w.z = cvt_pk(v[4], v[5]); w.w = cvt_pk(v[6], v[7]);
;                     *(v4u*)(Z + (size_t)row * NIN + c0) = w;
;                     if (wrA) {
;                         const int colA = c0 - (pn < 4 ? 512 : 1024);
;                         float* dst;
;                         if (samp) { const int rs = row - MP; dst = out + (pn < 4 ? O_AKS : O_AVS) + (size_t)l * 16 * 512 * 512 + ((size_t)((rs >> 6) * 512 + 448 + (rs & 63))) * 512 + colA; }
;                         else { const int sq = (row & 16383) - 15872; dst = out + (pn < 4 ? O_AKP : O_AVP) + (size_t)l * 2 * 512 * 512 + ((size_t)((row >> 14) * 512 + sq)) * 512 + colA; }
;                         *(f32x4*)dst = (f32x4){v[0], v[1], v[2], v[3]}; *(f32x4*)(dst + 4) = (f32x4){v[4], v[5], v[6], v[7]};
.LBB0_226:
	s_ashr_i32 s14, s36, 5
	s_and_b32 s56, s14, 0xfffffe00
	s_addk_i32 s56, 0xc200
	s_waitcnt lgkmcnt(5)
	v_add_u32_e32 v70, s56, v67
	s_lshl_b32 s53, s36, 3
	s_waitcnt lgkmcnt(4)
	v_ashrrev_i32_e32 v71, 31, v70
	s_add_i32 s53, s53, 0xfffc01c0
	v_lshlrev_b64 v[70:71], 11, v[70:71]
	v_lshl_add_u64 v[72:73], s[42:43], 0, v[70:71]
	v_or_b32_e32 v70, s53, v177
	v_ashrrev_i32_e32 v71, 31, v70
	s_waitcnt lgkmcnt(0)
	v_or_b32_e32 v74, s36, v177
	v_mov_b64_e32 v[68:69], s[66:67]
	v_lshlrev_b64 v[70:71], 11, v[70:71]
	v_mad_i64_i32 v[68:69], s[14:15], v74, s71, v[68:69]
	v_lshl_add_u64 v[80:81], s[30:31], 0, v[70:71]
	v_lshl_add_u64 v[70:71], v[146:147], 1, v[68:69]
	s_and_b64 vcc, exec, s[8:9]
	v_cndmask_b32_e64 v69, v73, v81, s[4:5]
	v_cndmask_b32_e64 v68, v72, v80, s[4:5]
	v_cvt_pk_bf16_f32 v76, v60, v61
	v_cvt_pk_bf16_f32 v77, v62, v63
	v_cvt_pk_bf16_f32 v78, v56, v57
	v_cvt_pk_bf16_f32 v79, v58, v59
	global_store_dwordx4 v[70:71], v[76:79], off sc1
	s_cbranch_vccnz .LBB0_228
	v_lshl_add_u64 v[72:73], v[148:149], 2, v[68:69]
	global_store_dwordx4 v[72:73], v[60:63], off sc1
	global_store_dwordx4 v[72:73], v[56:59], off offset:16 sc1
.LBB0_228:
	s_and_b32 s14, s84, 63
	s_cmp_eq_u32 s14, 63
	s_cselect_b64 s[14:15], -1, 0
	s_or_b64 s[14:15], s[4:5], s[14:15]
	s_and_b64 s[38:39], s[54:55], s[14:15]
	s_ashr_i32 s14, s36, 7
	s_and_b32 s84, s14, 0xffffff80
	s_lshl_b32 s57, s36, 1
	s_addk_i32 s84, 0xc080
	s_add_i32 s57, s57, 0xffff0040
	v_add_u32_e32 v72, s84, v67
	v_or_b32_e32 v76, s57, v177
	v_ashrrev_i32_e32 v73, 31, v72
	v_ashrrev_i32_e32 v77, 31, v76
	v_lshlrev_b64 v[72:73], 9, v[72:73]
	v_lshlrev_b64 v[76:77], 9, v[76:77]
	v_cndmask_b32_e64 v67, 0, 1, s[38:39]
	v_cmp_ne_u32_e64 s[14:15], 1, v67
	s_andn2_b64 vcc, exec, s[38:39]
	v_cndmask_b32_e64 v73, v73, v77, s[4:5]
	v_cndmask_b32_e64 v72, v72, v76, s[4:5]
	s_cbranch_vccnz .LBB0_230
	s_and_b64 s[36:37], s[4:5], exec
	s_cselect_b32 s36, 0xcc80000, s2
	s_add_u32 s36, s94, s36
	s_addc_u32 s37, s95, 0
	v_lshl_add_u64 v[76:77], s[36:37], 0, v[72:73]
	v_lshl_add_u64 v[76:77], v[144:145], 2, v[76:77]
	global_store_dwordx4 v[76:77], v[60:63], off sc1
	global_store_dwordx4 v[76:77], v[56:59], off offset:16 sc1

; __device__ __forceinline__ unsigned cvt_pk(float lo, float hi) { unsigned r; asm("v_cvt_pk_bf16_f32 %0, %1, %2" : "=v"(r) : "v"(lo), "v"(hi)); return r; }
;     __device__ __forceinline__ void operator()(AccRef acc, const pg8::Unit& u, int wr, int wc, int, int) const {
;     ...
;                     v4u w; w.x = cvt_pk(v[0], v[1]); w.y = cvt_pk(v[2], v[3]); w.z = cvt_pk(v[4], v[5]); w.w = cvt_pk(v[6], v[7]);
;                     *(v4u*)(Z + (size_t)row * NIN + c0) = w;
;                     if (wrA) {
;                         const int colA = c0 - (pn < 4 ? 512 : 1024);
;                         float* dst;
;                         if (samp) { const int rs = row - MP; dst = out + (pn < 4 ? O_AKS : O_AVS) + (size_t)l * 16 * 512 * 512 + ((size_t)((rs >> 6) * 512 + 448 + (rs & 63))) * 512 + colA; }
;                         else { const int sq = (row & 16383) - 15872; dst = out + (pn < 4 ? O_AKP : O_AVP) + (size_t)l * 2 * 512 * 512 + ((size_t)((row >> 14) * 512 + sq)) * 512 + colA; }
;                         *(f32x4*)dst = (f32x4){v[0], v[1], v[2], v[3]}; *(f32x4*)(dst + 4) = (f32x4){v[4], v[5], v[6], v[7]};
;                     }
;                     if (wrB && (samp || ai == 1)) {
;                         const int colB = c0 - (bj == 0 ? 2048 : 2176);
;                         float* dst;
;                         if (samp) { const int rs = row - MP; dst = out + (bj == 0 ? O_BKS : O_BVS) + (size_t)l * 16 * 128 * 128 + ((size_t)((rs >> 6) * 128 + 64 + (rs & 63))) * 128 + colB; }
;                         else { const int sq = (row & 16383) - 16256; dst = out + (bj == 0 ? O_BKP : O_BVP) + (size_t)l * 2 * 128 * 128 + ((size_t)((row >> 14) * 128 + sq)) * 128 + colB; }
;                         *(f32x4*)dst = (f32x4){v[0], v[1], v[2], v[3]}; *(f32x4*)(dst + 4) = (f32x4){v[4], v[5], v[6], v[7]};
;                     }
.LBB0_234:
	s_and_b64 vcc, exec, s[8:9]
	s_waitcnt lgkmcnt(3)
	v_cvt_pk_bf16_f32 v56, v52, v53
	s_waitcnt lgkmcnt(2)
	v_cvt_pk_bf16_f32 v57, v54, v55
	v_cvt_pk_bf16_f32 v58, v48, v49
	v_cvt_pk_bf16_f32 v59, v50, v51
	global_store_dwordx4 v[70:71], v[56:59], off offset:256 sc1
	s_cbranch_vccnz .LBB0_236
	s_nop 0
	v_lshl_add_u64 v[56:57], v[120:121], 2, v[68:69]
	global_store_dwordx4 v[56:57], v[52:55], off sc1
	global_store_dwordx4 v[56:57], v[48:51], off offset:16 sc1
.LBB0_236:
	s_and_b64 vcc, exec, s[14:15]
	s_cbranch_vccnz .LBB0_238
	s_and_b64 s[36:37], s[4:5], exec
	s_cselect_b32 s36, 0xce80000, s3
	s_add_u32 s36, s94, s36
	s_addc_u32 s37, s95, 0
	v_lshl_add_u64 v[56:57], s[36:37], 0, v[72:73]
	v_lshl_add_u64 v[56:57], v[144:145], 2, v[56:57]
	global_store_dwordx4 v[56:57], v[52:55], off sc1
	global_store_dwordx4 v[56:57], v[48:51], off offset:16 sc1

;     __device__ __forceinline__ void operator()(AccRef acc, const pg8::Unit& u, int wr, int wc, int, int) const {
;     ...
;                 const int row = pm * 256 + ai * 128 + wr * 64 + m * 16 + fr;
;                 const float rstd = __builtin_amdgcn_rsqf(sq[ai][m] * (1.0f / DM) + EPS) * (isq ? QSCALE : 1.0f);
;                 const int pos = samp ? 2048 + ((row - MP) & 63) : (row & 16383);
; #pragma unroll
;                 for (int bj = 0; bj < 2; ++bj) {
;                     const int c0 = pn * 256 + bj * 128 + wc * 32 + 8 * fq;
;                     float v[8];
; #pragma unroll
;                     for (int j = 0; j < 4; ++j) { v[j] = acc[ai][bj][m][0][j] * rstd; v[4 + j] = acc[ai][bj][m][1][j] * rstd; }
;                     const bool ropet = (pn == 6 || pn == 7 || (pn == 8 && bj == 0)) && ((wc & 1) == 0);
;                     if (ropet) {
;                         float pv[8];
; #pragma unroll
;                         for (int j = 0; j < 8; ++j) pv[j] = __shfl_xor(v[j], 16);
;                         if (fq < 2) {
;                             const f32x4* cs = (const f32x4*)(rope + (size_t)pos * 16);
;                             const float sg = (fq == 0) ? -1.f : 1.f;
; #pragma unroll
;                             for (int jj = 0; jj < 4; ++jj) { const f32x4 t = cs[jj];
;                                 v[2 * jj] = v[2 * jj] * t[0] + sg * pv[2 * jj] * t[1];
;                                 v[2 * jj + 1] = v[2 * jj + 1] * t[2] + sg * pv[2 * jj + 1] * t[3]; }
;                         }
;                     }
;                     v4u w; w.x = cvt_pk(v[0], v[1]); w.y = cvt_pk(v[2], v[3]); w.z = cvt_pk(v[4], v[5]); w.w = cvt_pk(v[6], v[7]);
;                     *(v4u*)(Z + (size_t)row * NIN + c0) = w;
;                     if (wrA) {
;                         const int colA = c0 - (pn < 4 ? 512 : 1024);
;                         float* dst;
;                         if (samp) { const int rs = row - MP; dst = out + (pn < 4 ? O_AKS : O_AVS) + (size_t)l * 16 * 512 * 512 + ((size_t)((rs >> 6) * 512 + 448 + (rs & 63))) * 512 + colA; }
;                         else { const int sq = (row & 16383) - 15872; dst = out + (pn < 4 ? O_AKP : O_AVP) + (size_t)l * 2 * 512 * 512 + ((size_t)((row >> 14) * 512 + sq)) * 512 + colA; }
;                         *(f32x4*)dst = (f32x4){v[0], v[1], v[2], v[3]}; *(f32x4*)(dst + 4) = (f32x4){v[4], v[5], v[6], v[7]};
.LBB0_242:
	s_waitcnt lgkmcnt(5)
	v_or_b32_e32 v54, 16, v74
	s_waitcnt lgkmcnt(2)
	v_mov_b64_e32 v[52:53], s[66:67]
	v_mad_i64_i32 v[52:53], s[36:37], v54, s71, v[52:53]
	v_add_u32_e32 v54, s56, v51
	v_ashrrev_i32_e32 v55, 31, v54
	v_lshlrev_b64 v[54:55], 11, v[54:55]
	v_lshl_add_u64 v[60:61], s[42:43], 0, v[54:55]
	v_or_b32_e32 v54, s53, v124
	v_ashrrev_i32_e32 v55, 31, v54
	v_lshlrev_b64 v[54:55], 11, v[54:55]
	s_waitcnt lgkmcnt(0)
	v_lshl_add_u64 v[62:63], s[30:31], 0, v[54:55]
	v_lshl_add_u64 v[54:55], v[146:147], 1, v[52:53]
	s_and_b64 vcc, exec, s[8:9]
	v_cndmask_b32_e64 v53, v61, v63, s[4:5]
	v_cndmask_b32_e64 v52, v60, v62, s[4:5]
	v_cvt_pk_bf16_f32 v56, v44, v45
	v_cvt_pk_bf16_f32 v57, v46, v47
	v_cvt_pk_bf16_f32 v58, v40, v41
	v_cvt_pk_bf16_f32 v59, v42, v43
	global_store_dwordx4 v[54:55], v[56:59], off sc1
	s_cbranch_vccnz .LBB0_244
	s_nop 0
	v_lshl_add_u64 v[56:57], v[148:149], 2, v[52:53]
	global_store_dwordx4 v[56:57], v[44:47], off sc1
	global_store_dwordx4 v[56:57], v[40:43], off offset:16 sc1
.LBB0_244:
	s_nop 0
	v_add_u32_e32 v56, s84, v51
	v_or_b32_e32 v58, s57, v124
	v_ashrrev_i32_e32 v57, 31, v56
	v_ashrrev_i32_e32 v59, 31, v58
	v_lshlrev_b64 v[56:57], 9, v[56:57]
	v_lshlrev_b64 v[58:59], 9, v[58:59]
	s_and_b64 vcc, exec, s[14:15]
	v_cndmask_b32_e64 v57, v57, v59, s[4:5]
	v_cndmask_b32_e64 v56, v56, v58, s[4:5]
	s_cbranch_vccnz .LBB0_246
	s_and_b64 s[36:37], s[4:5], exec
	s_cselect_b32 s36, 0xcc80000, s2
	s_add_u32 s36, s94, s36
	s_addc_u32 s37, s95, 0
	v_lshl_add_u64 v[58:59], s[36:37], 0, v[56:57]
	v_lshl_add_u64 v[58:59], v[144:145], 2, v[58:59]
	global_store_dwordx4 v[58:59], v[44:47], off sc1
	global_store_dwordx4 v[58:59], v[40:43], off offset:16 sc1

; __device__ __forceinline__ unsigned cvt_pk(float lo, float hi) { unsigned r; asm("v_cvt_pk_bf16_f32 %0, %1, %2" : "=v"(r) : "v"(lo), "v"(hi)); return r; }
;     __device__ __forceinline__ void operator()(AccRef acc, const pg8::Unit& u, int wr, int wc, int, int) const {
;     ...
;                     v4u w; w.x = cvt_pk(v[0], v[1]); w.y = cvt_pk(v[2], v[3]); w.z = cvt_pk(v[4], v[5]); w.w = cvt_pk(v[6], v[7]);
;                     *(v4u*)(Z + (size_t)row * NIN + c0) = w;
;                     if (wrA) {
;                         const int colA = c0 - (pn < 4 ? 512 : 1024);
;                         float* dst;
;                         if (samp) { const int rs = row - MP; dst = out + (pn < 4 ? O_AKS : O_AVS) + (size_t)l * 16 * 512 * 512 + ((size_t)((rs >> 6) * 512 + 448 + (rs & 63))) * 512 + colA; }
;                         else { const int sq = (row & 16383) - 15872; dst = out + (pn < 4 ? O_AKP : O_AVP) + (size_t)l * 2 * 512 * 512 + ((size_t)((row >> 14) * 512 + sq)) * 512 + colA; }
;                         *(f32x4*)dst = (f32x4){v[0], v[1], v[2], v[3]}; *(f32x4*)(dst + 4) = (f32x4){v[4], v[5], v[6], v[7]};
;                     }
;                     if (wrB && (samp || ai == 1)) {
;                         const int colB = c0 - (bj == 0 ? 2048 : 2176);
;                         float* dst;
;                         if (samp) { const int rs = row - MP; dst = out + (bj == 0 ? O_BKS : O_BVS) + (size_t)l * 16 * 128 * 128 + ((size_t)((rs >> 6) * 128 + 64 + (rs & 63))) * 128 + colB; }
;                         else { const int sq = (row & 16383) - 16256; dst = out + (bj == 0 ? O_BKP : O_BVP) + (size_t)l * 2 * 128 * 128 + ((size_t)((row >> 14) * 128 + sq)) * 128 + colB; }
;                         *(f32x4*)dst = (f32x4){v[0], v[1], v[2], v[3]}; *(f32x4*)(dst + 4) = (f32x4){v[4], v[5], v[6], v[7]};
;                     }
.LBB0_250:
	s_and_b64 vcc, exec, s[8:9]
	s_waitcnt lgkmcnt(3)
	v_cvt_pk_bf16_f32 v40, v36, v37
	s_waitcnt lgkmcnt(2)
	v_cvt_pk_bf16_f32 v41, v38, v39
	v_cvt_pk_bf16_f32 v42, v32, v33
	v_cvt_pk_bf16_f32 v43, v34, v35
	global_store_dwordx4 v[54:55], v[40:43], off offset:256 sc1
	s_cbranch_vccnz .LBB0_252
	s_nop 0
	v_lshl_add_u64 v[40:41], v[120:121], 2, v[52:53]
	global_store_dwordx4 v[40:41], v[36:39], off sc1
	global_store_dwordx4 v[40:41], v[32:35], off offset:16 sc1
.LBB0_252:
	s_and_b64 vcc, exec, s[14:15]
	s_cbranch_vccnz .LBB0_254
	s_and_b64 s[36:37], s[4:5], exec
	s_cselect_b32 s36, 0xce80000, s3
	s_add_u32 s36, s94, s36
	s_addc_u32 s37, s95, 0
	v_lshl_add_u64 v[40:41], s[36:37], 0, v[56:57]
	v_lshl_add_u64 v[40:41], v[144:145], 2, v[40:41]
	global_store_dwordx4 v[40:41], v[36:39], off sc1
	global_store_dwordx4 v[40:41], v[32:35], off offset:16 sc1

;     __device__ __forceinline__ void operator()(AccRef acc, const pg8::Unit& u, int wr, int wc, int, int) const {
;     ...
;                 const int row = pm * 256 + ai * 128 + wr * 64 + m * 16 + fr;
;                 const float rstd = __builtin_amdgcn_rsqf(sq[ai][m] * (1.0f / DM) + EPS) * (isq ? QSCALE : 1.0f);
;                 const int pos = samp ? 2048 + ((row - MP) & 63) : (row & 16383);
; #pragma unroll
;                 for (int bj = 0; bj < 2; ++bj) {
;                     const int c0 = pn * 256 + bj * 128 + wc * 32 + 8 * fq;
;                     float v[8];
; #pragma unroll
;                     for (int j = 0; j < 4; ++j) { v[j] = acc[ai][bj][m][0][j] * rstd; v[4 + j] = acc[ai][bj][m][1][j] * rstd; }
;                     const bool ropet = (pn == 6 || pn == 7 || (pn == 8 && bj == 0)) && ((wc & 1) == 0);
;                     if (ropet) {
;                         float pv[8];
; #pragma unroll
;                         for (int j = 0; j < 8; ++j) pv[j] = __shfl_xor(v[j], 16);
;                         if (fq < 2) {
;                             const f32x4* cs = (const f32x4*)(rope + (size_t)pos * 16);
;                             const float sg = (fq == 0) ? -1.f : 1.f;
; #pragma unroll
;                             for (int jj = 0; jj < 4; ++jj) { const f32x4 t = cs[jj];
;                                 v[2 * jj] = v[2 * jj] * t[0] + sg * pv[2 * jj] * t[1];
;                                 v[2 * jj + 1] = v[2 * jj + 1] * t[2] + sg * pv[2 * jj + 1] * t[3]; }
;                         }
;                     }
;                     v4u w; w.x = cvt_pk(v[0], v[1]); w.y = cvt_pk(v[2], v[3]); w.z = cvt_pk(v[4], v[5]); w.w = cvt_pk(v[6], v[7]);
;                     *(v4u*)(Z + (size_t)row * NIN + c0) = w;
;                     if (wrA) {
;                         const int colA = c0 - (pn < 4 ? 512 : 1024);
;                         float* dst;
;                         if (samp) { const int rs = row - MP; dst = out + (pn < 4 ? O_AKS : O_AVS) + (size_t)l * 16 * 512 * 512 + ((size_t)((rs >> 6) * 512 + 448 + (rs & 63))) * 512 + colA; }
;                         else { const int sq = (row & 16383) - 15872; dst = out + (pn < 4 ? O_AKP : O_AVP) + (size_t)l * 2 * 512 * 512 + ((size_t)((row >> 14) * 512 + sq)) * 512 + colA; }
;                         *(f32x4*)dst = (f32x4){v[0], v[1], v[2], v[3]}; *(f32x4*)(dst + 4) = (f32x4){v[4], v[5], v[6], v[7]};
.LBB0_258:
	s_waitcnt lgkmcnt(5)
	v_or_b32_e32 v38, 32, v74
	s_waitcnt lgkmcnt(2)
	v_mov_b64_e32 v[36:37], s[66:67]
	v_mad_i64_i32 v[36:37], s[36:37], v38, s71, v[36:37]
	v_add_u32_e32 v38, s56, v35
	v_ashrrev_i32_e32 v39, 31, v38
	v_lshlrev_b64 v[38:39], 11, v[38:39]
	v_lshl_add_u64 v[44:45], s[42:43], 0, v[38:39]
	v_or_b32_e32 v38, s53, v106
	v_ashrrev_i32_e32 v39, 31, v38
	v_lshlrev_b64 v[38:39], 11, v[38:39]
	s_waitcnt lgkmcnt(0)
	v_lshl_add_u64 v[46:47], s[30:31], 0, v[38:39]
	v_lshl_add_u64 v[38:39], v[146:147], 1, v[36:37]
	s_and_b64 vcc, exec, s[8:9]
	v_cndmask_b32_e64 v37, v45, v47, s[4:5]
	v_cndmask_b32_e64 v36, v44, v46, s[4:5]
	v_cvt_pk_bf16_f32 v40, v28, v29
	v_cvt_pk_bf16_f32 v41, v30, v31
	v_cvt_pk_bf16_f32 v42, v24, v25
	v_cvt_pk_bf16_f32 v43, v26, v27
	global_store_dwordx4 v[38:39], v[40:43], off sc1
	s_cbranch_vccnz .LBB0_260
	s_nop 0
	v_lshl_add_u64 v[40:41], v[148:149], 2, v[36:37]
	global_store_dwordx4 v[40:41], v[28:31], off sc1
	global_store_dwordx4 v[40:41], v[24:27], off offset:16 sc1
.LBB0_260:
	s_nop 0
	v_add_u32_e32 v40, s84, v35
	v_or_b32_e32 v42, s57, v106
	v_ashrrev_i32_e32 v41, 31, v40
	v_ashrrev_i32_e32 v43, 31, v42
	v_lshlrev_b64 v[40:41], 9, v[40:41]
	v_lshlrev_b64 v[42:43], 9, v[42:43]
	s_and_b64 vcc, exec, s[14:15]
	v_cndmask_b32_e64 v41, v41, v43, s[4:5]
	v_cndmask_b32_e64 v40, v40, v42, s[4:5]
	s_cbranch_vccnz .LBB0_262
	s_and_b64 s[36:37], s[4:5], exec
	s_cselect_b32 s36, 0xcc80000, s2
	s_add_u32 s36, s94, s36
	s_addc_u32 s37, s95, 0
	v_lshl_add_u64 v[42:43], s[36:37], 0, v[40:41]
	v_lshl_add_u64 v[42:43], v[144:145], 2, v[42:43]
	global_store_dwordx4 v[42:43], v[28:31], off sc1
	global_store_dwordx4 v[42:43], v[24:27], off offset:16 sc1

; __device__ __forceinline__ unsigned cvt_pk(float lo, float hi) { unsigned r; asm("v_cvt_pk_bf16_f32 %0, %1, %2" : "=v"(r) : "v"(lo), "v"(hi)); return r; }
;     __device__ __forceinline__ void operator()(AccRef acc, const pg8::Unit& u, int wr, int wc, int, int) const {
;     ...
;                     v4u w; w.x = cvt_pk(v[0], v[1]); w.y = cvt_pk(v[2], v[3]); w.z = cvt_pk(v[4], v[5]); w.w = cvt_pk(v[6], v[7]);
;                     *(v4u*)(Z + (size_t)row * NIN + c0) = w;
;                     if (wrA) {
;                         const int colA = c0 - (pn < 4 ? 512 : 1024);
;                         float* dst;
;                         if (samp) { const int rs = row - MP; dst = out + (pn < 4 ? O_AKS : O_AVS) + (size_t)l * 16 * 512 * 512 + ((size_t)((rs >> 6) * 512 + 448 + (rs & 63))) * 512 + colA; }
;                         else { const int sq = (row & 16383) - 15872; dst = out + (pn < 4 ? O_AKP : O_AVP) + (size_t)l * 2 * 512 * 512 + ((size_t)((row >> 14) * 512 + sq)) * 512 + colA; }
;                         *(f32x4*)dst = (f32x4){v[0], v[1], v[2], v[3]}; *(f32x4*)(dst + 4) = (f32x4){v[4], v[5], v[6], v[7]};
;                     }
;                     if (wrB && (samp || ai == 1)) {
;                         const int colB = c0 - (bj == 0 ? 2048 : 2176);
;                         float* dst;
;                         if (samp) { const int rs = row - MP; dst = out + (bj == 0 ? O_BKS : O_BVS) + (size_t)l * 16 * 128 * 128 + ((size_t)((rs >> 6) * 128 + 64 + (rs & 63))) * 128 + colB; }
;                         else { const int sq = (row & 16383) - 16256; dst = out + (bj == 0 ? O_BKP : O_BVP) + (size_t)l * 2 * 128 * 128 + ((size_t)((row >> 14) * 128 + sq)) * 128 + colB; }
;                         *(f32x4*)dst = (f32x4){v[0], v[1], v[2], v[3]}; *(f32x4*)(dst + 4) = (f32x4){v[4], v[5], v[6], v[7]};
;                     }
.LBB0_266:
	s_and_b64 vcc, exec, s[8:9]
	s_waitcnt lgkmcnt(3)
	v_cvt_pk_bf16_f32 v24, v20, v21
	s_waitcnt lgkmcnt(2)
	v_cvt_pk_bf16_f32 v25, v22, v23
	v_cvt_pk_bf16_f32 v26, v16, v17
	v_cvt_pk_bf16_f32 v27, v18, v19
	global_store_dwordx4 v[38:39], v[24:27], off offset:256 sc1
	s_cbranch_vccnz .LBB0_268
	s_nop 0
	v_lshl_add_u64 v[24:25], v[120:121], 2, v[36:37]
	global_store_dwordx4 v[24:25], v[20:23], off sc1
	global_store_dwordx4 v[24:25], v[16:19], off offset:16 sc1
.LBB0_268:
	s_and_b64 vcc, exec, s[14:15]
	s_cbranch_vccnz .LBB0_270
	s_and_b64 s[36:37], s[4:5], exec
	s_cselect_b32 s36, 0xce80000, s3
	s_add_u32 s36, s94, s36
	s_addc_u32 s37, s95, 0
	v_lshl_add_u64 v[24:25], s[36:37], 0, v[40:41]
	v_lshl_add_u64 v[24:25], v[144:145], 2, v[24:25]
	global_store_dwordx4 v[24:25], v[20:23], off sc1
	global_store_dwordx4 v[24:25], v[16:19], off offset:16 sc1

;     __device__ __forceinline__ void operator()(AccRef acc, const pg8::Unit& u, int wr, int wc, int, int) const {
;     ...
;                 const int row = pm * 256 + ai * 128 + wr * 64 + m * 16 + fr;
;                 const float rstd = __builtin_amdgcn_rsqf(sq[ai][m] * (1.0f / DM) + EPS) * (isq ? QSCALE : 1.0f);
;                 const int pos = samp ? 2048 + ((row - MP) & 63) : (row & 16383);
; #pragma unroll
;                 for (int bj = 0; bj < 2; ++bj) {
;                     const int c0 = pn * 256 + bj * 128 + wc * 32 + 8 * fq;
;                     float v[8];
; #pragma unroll
;                     for (int j = 0; j < 4; ++j) { v[j] = acc[ai][bj][m][0][j] * rstd; v[4 + j] = acc[ai][bj][m][1][j] * rstd; }
;                     const bool ropet = (pn == 6 || pn == 7 || (pn == 8 && bj == 0)) && ((wc & 1) == 0);
;                     if (ropet) {
;                         float pv[8];
; #pragma unroll
;                         for (int j = 0; j < 8; ++j) pv[j] = __shfl_xor(v[j], 16);
;                         if (fq < 2) {
;                             const f32x4* cs = (const f32x4*)(rope + (size_t)pos * 16);
;                             const float sg = (fq == 0) ? -1.f : 1.f;
; #pragma unroll
;                             for (int jj = 0; jj < 4; ++jj) { const f32x4 t = cs[jj];
;                                 v[2 * jj] = v[2 * jj] * t[0] + sg * pv[2 * jj] * t[1];
;                                 v[2 * jj + 1] = v[2 * jj + 1] * t[2] + sg * pv[2 * jj + 1] * t[3]; }
;                         }
;                     }
;                     v4u w; w.x = cvt_pk(v[0], v[1]); w.y = cvt_pk(v[2], v[3]); w.z = cvt_pk(v[4], v[5]); w.w = cvt_pk(v[6], v[7]);
;                     *(v4u*)(Z + (size_t)row * NIN + c0) = w;
;                     if (wrA) {
;                         const int colA = c0 - (pn < 4 ? 512 : 1024);
;                         float* dst;
;                         if (samp) { const int rs = row - MP; dst = out + (pn < 4 ? O_AKS : O_AVS) + (size_t)l * 16 * 512 * 512 + ((size_t)((rs >> 6) * 512 + 448 + (rs & 63))) * 512 + colA; }
;                         else { const int sq = (row & 16383) - 15872; dst = out + (pn < 4 ? O_AKP : O_AVP) + (size_t)l * 2 * 512 * 512 + ((size_t)((row >> 14) * 512 + sq)) * 512 + colA; }
;                         *(f32x4*)dst = (f32x4){v[0], v[1], v[2], v[3]}; *(f32x4*)(dst + 4) = (f32x4){v[4], v[5], v[6], v[7]};
.LBB0_274:
	s_waitcnt lgkmcnt(5)
	v_or_b32_e32 v22, 48, v74
	s_waitcnt lgkmcnt(2)
	v_mov_b64_e32 v[20:21], s[66:67]
	v_mad_i64_i32 v[20:21], s[10:11], v22, s71, v[20:21]
	v_add_u32_e32 v22, s56, v19
	v_ashrrev_i32_e32 v23, 31, v22
	v_lshlrev_b64 v[22:23], 11, v[22:23]
	v_lshl_add_u64 v[28:29], s[42:43], 0, v[22:23]
	v_or_b32_e32 v22, s53, v90
	v_ashrrev_i32_e32 v23, 31, v22
	v_lshlrev_b64 v[22:23], 11, v[22:23]
	s_waitcnt lgkmcnt(0)
	v_lshl_add_u64 v[30:31], s[30:31], 0, v[22:23]
	v_lshl_add_u64 v[22:23], v[146:147], 1, v[20:21]
	s_and_b64 vcc, exec, s[8:9]
	v_cndmask_b32_e64 v21, v29, v31, s[4:5]
	v_cndmask_b32_e64 v20, v28, v30, s[4:5]
	v_cvt_pk_bf16_f32 v24, v12, v13
	v_cvt_pk_bf16_f32 v25, v14, v15
	v_cvt_pk_bf16_f32 v26, v8, v9
	v_cvt_pk_bf16_f32 v27, v10, v11
	global_store_dwordx4 v[22:23], v[24:27], off sc1
	s_cbranch_vccnz .LBB0_276
	s_nop 0
	v_lshl_add_u64 v[24:25], v[148:149], 2, v[20:21]
	global_store_dwordx4 v[24:25], v[12:15], off sc1
	global_store_dwordx4 v[24:25], v[8:11], off offset:16 sc1
.LBB0_276:
	s_nop 0
	v_add_u32_e32 v24, s84, v19
	v_or_b32_e32 v26, s57, v90
	v_ashrrev_i32_e32 v25, 31, v24
	v_ashrrev_i32_e32 v27, 31, v26
	v_lshlrev_b64 v[24:25], 9, v[24:25]
	v_lshlrev_b64 v[26:27], 9, v[26:27]
	s_and_b64 vcc, exec, s[14:15]
	v_cndmask_b32_e64 v25, v25, v27, s[4:5]
	v_cndmask_b32_e64 v24, v24, v26, s[4:5]
	s_cbranch_vccnz .LBB0_278
	s_and_b64 s[10:11], s[4:5], exec
	s_cselect_b32 s10, 0xcc80000, s2
	s_add_u32 s10, s94, s10
	s_addc_u32 s11, s95, 0
	v_lshl_add_u64 v[26:27], s[10:11], 0, v[24:25]
	v_lshl_add_u64 v[26:27], v[144:145], 2, v[26:27]
	global_store_dwordx4 v[26:27], v[12:15], off sc1
	global_store_dwordx4 v[26:27], v[8:11], off offset:16 sc1

; __device__ __forceinline__ unsigned cvt_pk(float lo, float hi) { unsigned r; asm("v_cvt_pk_bf16_f32 %0, %1, %2" : "=v"(r) : "v"(lo), "v"(hi)); return r; }
;     __device__ __forceinline__ void operator()(AccRef acc, const pg8::Unit& u, int wr, int wc, int, int) const {
;     ...
;                     v4u w; w.x = cvt_pk(v[0], v[1]); w.y = cvt_pk(v[2], v[3]); w.z = cvt_pk(v[4], v[5]); w.w = cvt_pk(v[6], v[7]);
;                     *(v4u*)(Z + (size_t)row * NIN + c0) = w;
;                     if (wrA) {
;                         const int colA = c0 - (pn < 4 ? 512 : 1024);
;                         float* dst;
;                         if (samp) { const int rs = row - MP; dst = out + (pn < 4 ? O_AKS : O_AVS) + (size_t)l * 16 * 512 * 512 + ((size_t)((rs >> 6) * 512 + 448 + (rs & 63))) * 512 + colA; }
;                         else { const int sq = (row & 16383) - 15872; dst = out + (pn < 4 ? O_AKP : O_AVP) + (size_t)l * 2 * 512 * 512 + ((size_t)((row >> 14) * 512 + sq)) * 512 + colA; }
;                         *(f32x4*)dst = (f32x4){v[0], v[1], v[2], v[3]}; *(f32x4*)(dst + 4) = (f32x4){v[4], v[5], v[6], v[7]};
;                     }
;                     if (wrB && (samp || ai == 1)) {
;                         const int colB = c0 - (bj == 0 ? 2048 : 2176);
;                         float* dst;
;                         if (samp) { const int rs = row - MP; dst = out + (bj == 0 ? O_BKS : O_BVS) + (size_t)l * 16 * 128 * 128 + ((size_t)((rs >> 6) * 128 + 64 + (rs & 63))) * 128 + colB; }
;                         else { const int sq = (row & 16383) - 16256; dst = out + (bj == 0 ? O_BKP : O_BVP) + (size_t)l * 2 * 128 * 128 + ((size_t)((row >> 14) * 128 + sq)) * 128 + colB; }
;                         *(f32x4*)dst = (f32x4){v[0], v[1], v[2], v[3]}; *(f32x4*)(dst + 4) = (f32x4){v[4], v[5], v[6], v[7]};
;                     }
.LBB0_282:
	s_and_b64 vcc, exec, s[8:9]
	s_waitcnt lgkmcnt(3)
	v_cvt_pk_bf16_f32 v8, v4, v5
	s_waitcnt lgkmcnt(2)
	v_cvt_pk_bf16_f32 v9, v6, v7
	v_cvt_pk_bf16_f32 v10, v0, v1
	v_cvt_pk_bf16_f32 v11, v2, v3
	global_store_dwordx4 v[22:23], v[8:11], off offset:256 sc1
	s_cbranch_vccz .LBB0_285
	s_and_b64 vcc, exec, s[14:15]
	s_cbranch_vccz .LBB0_286

; template <int KK, class Epi, class Sched, bool ALIGN_EPI = true>
; __device__ __forceinline__ void gemm_phase(LAS unsigned char* lds, const bf16* gA, const bf16* gBt, const Sched& S, const Epi& E, const int wid) {
;     ...
;         if (!has_next) break;
; #pragma unroll
;         for (int a = 0; a < 2; ++a)
; #pragma unroll
;             for (int b = 0; b < 2; ++b)
; #pragma unroll
;                 for (int m = 0; m < 4; ++m)
; #pragma unroll
;                     for (int n = 0; n < 2; ++n) acc[a][b][m][n] = (f32x4){0.f, 0.f, 0.f, 0.f};
;         cur = nxt; cA = nA; cB = nB; ++ui;
;     __device__ __forceinline__ void operator()(AccRef acc, const pg8::Unit& u, int wr, int wc, int, int) const {
;     ...
;                     if (wrA) {
;                         const int colA = c0 - (pn < 4 ? 512 : 1024);
;                         float* dst;
;                         if (samp) { const int rs = row - MP; dst = out + (pn < 4 ? O_AKS : O_AVS) + (size_t)l * 16 * 512 * 512 + ((size_t)((rs >> 6) * 512 + 448 + (rs & 63))) * 512 + colA; }
;                         else { const int sq = (row & 16383) - 15872; dst = out + (pn < 4 ? O_AKP : O_AVP) + (size_t)l * 2 * 512 * 512 + ((size_t)((row >> 14) * 512 + sq)) * 512 + colA; }
;                         *(f32x4*)dst = (f32x4){v[0], v[1], v[2], v[3]}; *(f32x4*)(dst + 4) = (f32x4){v[4], v[5], v[6], v[7]};
;                     }
;                     if (wrB && (samp || ai == 1)) {
;                         const int colB = c0 - (bj == 0 ? 2048 : 2176);
;                         float* dst;
;                         if (samp) { const int rs = row - MP; dst = out + (bj == 0 ? O_BKS : O_BVS) + (size_t)l * 16 * 128 * 128 + ((size_t)((rs >> 6) * 128 + 64 + (rs & 63))) * 128 + colB; }
;                         else { const int sq = (row & 16383) - 16256; dst = out + (bj == 0 ? O_BKP : O_BVP) + (size_t)l * 2 * 128 * 128 + ((size_t)((row >> 14) * 128 + sq)) * 128 + colB; }
;                         *(f32x4*)dst = (f32x4){v[0], v[1], v[2], v[3]}; *(f32x4*)(dst + 4) = (f32x4){v[4], v[5], v[6], v[7]};
;                     }
.LBB0_285:
	s_nop 0
	v_lshl_add_u64 v[8:9], v[120:121], 2, v[20:21]
	global_store_dwordx4 v[8:9], v[4:7], off sc1
	global_store_dwordx4 v[8:9], v[0:3], off offset:16 sc1
	s_and_b64 vcc, exec, s[14:15]
	s_cbranch_vccnz .LBB0_284
.LBB0_286:
	s_and_b64 s[4:5], s[4:5], exec
	s_cselect_b32 s4, 0xce80000, s3
	s_add_u32 s4, s94, s4
	s_addc_u32 s5, s95, 0
	v_lshl_add_u64 v[8:9], s[4:5], 0, v[24:25]
	v_lshl_add_u64 v[8:9], v[144:145], 2, v[8:9]
	global_store_dwordx4 v[8:9], v[4:7], off sc1
	global_store_dwordx4 v[8:9], v[0:3], off offset:16 sc1
	s_andn2_b64 vcc, exec, s[88:89]
	s_mov_b64 s[4:5], -1
	s_cbranch_vccnz .LBB0_148

; __device__ __forceinline__ unsigned cvt_pk(float lo, float hi) { unsigned r; asm("v_cvt_pk_bf16_f32 %0, %1, %2" : "=v"(r) : "v"(lo), "v"(hi)); return r; }
;     ...
;     for (size_t i = gtid * 8; i < NA; i += gth * 8) {
;         const size_t gi = (size_t)l * NA + i;
;         const f32x4 a = *(const f32x4*)(I.cak + gi), b = *(const f32x4*)(I.cak + gi + 4), c = *(const f32x4*)(I.cav + gi), d = *(const f32x4*)(I.cav + gi + 4);
;         v4u w; w.x = cvt_pk(a[0], a[1]); w.y = cvt_pk(a[2], a[3]); w.z = cvt_pk(b[0], b[1]); w.w = cvt_pk(b[2], b[3]);
;         *(v4u*)((bf16*)(ws + WS_CKA) + gi) = w;
;         w.x = cvt_pk(c[0], c[1]); w.y = cvt_pk(c[2], c[3]); w.z = cvt_pk(d[0], d[1]); w.w = cvt_pk(d[2], d[3]);
;         *(v4u*)((bf16*)(ws + WS_CVA) + gi) = w;
;         if (((i >> 9) & 511) >= 64) { float* dk = out + O_AKS + gi - 32768; float* dv = out + O_AVS + gi - 32768;
;             *(f32x4*)dk = a; *(f32x4*)(dk + 4) = b; *(f32x4*)dv = c; *(f32x4*)(dv + 4) = d; }
;     }
.LBB0_294:
	v_lshl_add_u64 v[0:1], s[12:13], 0, v[18:19]
	global_load_dwordx4 v[4:7], v[0:1], off offset:-16 nt
	s_nop 0
	global_load_dwordx4 v[0:3], v[0:1], off nt
	v_lshl_add_u64 v[8:9], s[14:15], 0, v[18:19]
	s_waitcnt lgkmcnt(0)
	global_load_dwordx4 v[12:15], v[8:9], off offset:-16 nt
	s_nop 0
	global_load_dwordx4 v[8:11], v[8:9], off nt
	v_add_co_u32_e32 v36, vcc, 0x1000000, v22
	v_and_b32_e32 v24, 0x38000, v26
	s_nop 0
	v_addc_co_u32_e32 v37, vcc, 0, v23, vcc
	v_cmp_ne_u64_e32 vcc, 0, v[24:25]
	s_waitcnt vmcnt(3)
	v_cvt_pk_bf16_f32 v28, v4, v5
	v_cvt_pk_bf16_f32 v29, v6, v7
	s_waitcnt vmcnt(2)
	v_cvt_pk_bf16_f32 v30, v0, v1
	v_cvt_pk_bf16_f32 v31, v2, v3
	s_waitcnt vmcnt(1)
	v_cvt_pk_bf16_f32 v32, v12, v13
	v_cvt_pk_bf16_f32 v33, v14, v15
	s_waitcnt vmcnt(0)
	v_cvt_pk_bf16_f32 v34, v8, v9
	v_cvt_pk_bf16_f32 v35, v10, v11
	global_store_dwordx4 v[22:23], v[28:31], off sc1
	global_store_dwordx4 v[36:37], v[32:35], off sc1
	s_and_saveexec_b64 s[52:53], vcc
	s_cbranch_execz .LBB0_293
	v_lshl_add_u64 v[28:29], s[42:43], 0, v[18:19]
	v_add_co_u32_e32 v30, vcc, 0x8c60000, v28
	s_nop 1
	v_addc_co_u32_e32 v31, vcc, 0, v29, vcc
	global_store_dwordx4 v[30:31], v[4:7], off nt
	global_store_dwordx4 v[30:31], v[0:3], off offset:16 nt
	s_nop 1
	v_add_co_u32_e32 v0, vcc, 0xac60000, v28
	s_nop 1
	v_addc_co_u32_e32 v1, vcc, 0, v29, vcc
	global_store_dwordx4 v[0:1], v[12:15], off nt
	global_store_dwordx4 v[0:1], v[8:11], off offset:16 nt
	s_branch .LBB0_293

;     __device__ __forceinline__ void operator()(AccRef acc, const pg8::Unit& u, int wr, int wc, int, int) const {
;     ...
;                 const int row = pm * 256 + ai * 128 + wr * 64 + m * 16 + fr;
;                 const float rstd = __builtin_amdgcn_rsqf(sq[ai][m] * (1.0f / DM) + EPS) * (isq ? QSCALE : 1.0f);
;                 const int pos = samp ? 2048 + ((row - MP) & 63) : (row & 16383);
; #pragma unroll
;                 for (int bj = 0; bj < 2; ++bj) {
;                     const int c0 = pn * 256 + bj * 128 + wc * 32 + 8 * fq;
;                     float v[8];
; #pragma unroll
;                     for (int j = 0; j < 4; ++j) { v[j] = acc[ai][bj][m][0][j] * rstd; v[4 + j] = acc[ai][bj][m][1][j] * rstd; }
;                     const bool ropet = (pn == 6 || pn == 7 || (pn == 8 && bj == 0)) && ((wc & 1) == 0);
;                     if (ropet) {
;                         float pv[8];
; #pragma unroll
;                         for (int j = 0; j < 8; ++j) pv[j] = __shfl_xor(v[j], 16);
;                         if (fq < 2) {
;                             const f32x4* cs = (const f32x4*)(rope + (size_t)pos * 16);
;                             const float sg = (fq == 0) ? -1.f : 1.f;
; #pragma unroll
;                             for (int jj = 0; jj < 4; ++jj) { const f32x4 t = cs[jj];
;                                 v[2 * jj] = v[2 * jj] * t[0] + sg * pv[2 * jj] * t[1];
;                                 v[2 * jj + 1] = v[2 * jj + 1] * t[2] + sg * pv[2 * jj + 1] * t[3]; }
;                         }
;                     }
;                     v4u w; w.x = cvt_pk(v[0], v[1]); w.y = cvt_pk(v[2], v[3]); w.z = cvt_pk(v[4], v[5]); w.w = cvt_pk(v[6], v[7]);
;                     *(v4u*)(Z + (size_t)row * NIN + c0) = w;
;                     if (wrA) {
;                         const int colA = c0 - (pn < 4 ? 512 : 1024);
;                         float* dst;
;                         if (samp) { const int rs = row - MP; dst = out + (pn < 4 ? O_AKS : O_AVS) + (size_t)l * 16 * 512 * 512 + ((size_t)((rs >> 6) * 512 + 448 + (rs & 63))) * 512 + colA; }
;                         else { const int sq = (row & 16383) - 15872; dst = out + (pn < 4 ? O_AKP : O_AVP) + (size_t)l * 2 * 512 * 512 + ((size_t)((row >> 14) * 512 + sq)) * 512 + colA; }
;                         *(f32x4*)dst = (f32x4){v[0], v[1], v[2], v[3]}; *(f32x4*)(dst + 4) = (f32x4){v[4], v[5], v[6], v[7]};
.LBB0_910:
	s_add_u32 s78, s10, 0xba00000
	s_addc_u32 s79, s11, 0
	s_add_i32 s3, s14, -2
	s_cmp_lt_u32 s3, 4
	s_cselect_b64 s[10:11], -1, 0
	s_and_b32 s3, s66, 62
	s_cmp_eq_u32 s3, 62
	s_cselect_b64 s[16:17], -1, 0
	s_or_b64 s[16:17], s[6:7], s[16:17]
	s_and_b64 s[16:17], s[10:11], s[16:17]
	s_lshl_b32 s3, s14, 8
	v_readlane_b32 s10, v249, 44
	s_or_b32 s3, s3, s10
	s_waitcnt lgkmcnt(3)
	v_lshl_add_u32 v146, v145, 3, s3
	s_cmp_lt_i32 s14, 4
	s_movk_i32 s3, 0xfe00
	s_cselect_b32 s60, s3, 0xfffffc00
	s_mov_b32 s3, 0x8400000
	s_cselect_b32 s3, s3, 0x8800000
	s_mov_b32 s10, 0x8c80000
	s_cselect_b32 s10, s10, 0xac80000
	s_add_u32 s82, s58, s3
	s_addc_u32 s83, s59, 0
	s_add_u32 s80, s58, s10
	s_addc_u32 s81, s59, 0
	s_ashr_i32 s3, s2, 5
	s_and_b32 s49, s3, 0xfffffe00
	s_addk_i32 s49, 0xc200
	v_mov_b64_e32 v[148:149], s[78:79]
	v_mad_i64_i32 v[144:145], s[10:11], v144, s63, v[148:149]
	v_add_u32_e32 v148, s49, v157
	s_lshl_b32 s3, s2, 3
	v_ashrrev_i32_e32 v149, 31, v148
	s_add_i32 s3, s3, 0xfffc01c0
	v_lshlrev_b64 v[148:149], 11, v[148:149]
	v_lshl_add_u64 v[160:161], s[82:83], 0, v[148:149]
	v_or_b32_e32 v148, s3, v173
	v_ashrrev_i32_e32 v149, 31, v148
	v_lshlrev_b64 v[148:149], 11, v[148:149]
	v_lshl_add_u64 v[164:165], s[80:81], 0, v[148:149]
	s_waitcnt lgkmcnt(2)
	v_ashrrev_i32_e32 v147, 31, v146
	s_waitcnt lgkmcnt(0)
	v_cndmask_b32_e64 v136, 0, 1, s[16:17]
	v_add_u32_e32 v148, s60, v146
	v_lshl_add_u64 v[162:163], v[146:147], 1, v[144:145]
	v_cmp_ne_u32_e64 s[10:11], 1, v136
	s_andn2_b64 vcc, exec, s[16:17]
	v_cndmask_b32_e64 v161, v161, v165, s[6:7]
	v_cndmask_b32_e64 v160, v160, v164, s[6:7]
	v_ashrrev_i32_e32 v149, 31, v148
	v_cvt_pk_bf16_f32 v180, v124, v125
	v_cvt_pk_bf16_f32 v181, v126, v127
	v_cvt_pk_bf16_f32 v182, v120, v121
	v_cvt_pk_bf16_f32 v183, v122, v123
	global_store_dwordx4 v[162:163], v[180:183], off sc1
	s_cbranch_vccnz .LBB0_912
	s_and_b64 s[16:17], s[6:7], exec
	s_cselect_b32 s36, s68, 0x200000
	v_lshl_add_u64 v[144:145], v[160:161], 0, s[36:37]
	v_lshl_add_u64 v[144:145], v[148:149], 2, v[144:145]
	global_store_dwordx4 v[144:145], v[124:127], off sc1
	global_store_dwordx4 v[144:145], v[120:123], off offset:16 sc1
.LBB0_912:
	s_cmp_eq_u32 s14, 8
	s_cselect_b64 s[30:31], -1, 0
	s_lshl_b32 s51, s2, 1
	s_add_i32 s51, s51, 0xffff0040
	v_or_b32_e32 v144, s51, v173
	v_ashrrev_i32_e32 v145, 31, v144
	v_lshlrev_b64 v[144:145], 9, v[144:145]
	s_and_b64 s[14:15], s[30:31], s[6:7]
	v_cndmask_b32_e64 v136, 0, 1, s[14:15]
	v_lshl_add_u64 v[164:165], s[58:59], 0, v[144:145]
	v_add_u32_e32 v144, 0xfffff800, v146
	v_cmp_ne_u32_e64 s[16:17], 1, v136
	s_andn2_b64 vcc, exec, s[14:15]
	v_ashrrev_i32_e32 v145, 31, v144
	s_cbranch_vccnz .LBB0_914
	v_lshl_add_u64 v[180:181], v[144:145], 2, v[164:165]
	v_lshl_add_u64 v[182:183], v[180:181], 0, s[44:45]
	v_add_co_u32_e32 v180, vcc, 0xcd80000, v180
	s_nop 1
	v_addc_co_u32_e32 v181, vcc, 0, v181, vcc
	global_store_dwordx4 v[180:181], v[124:127], off sc1
	global_store_dwordx4 v[182:183], v[120:123], off offset:16 sc1

; __device__ __forceinline__ unsigned cvt_pk(float lo, float hi) { unsigned r; asm("v_cvt_pk_bf16_f32 %0, %1, %2" : "=v"(r) : "v"(lo), "v"(hi)); return r; }
;     __device__ __forceinline__ void operator()(AccRef acc, const pg8::Unit& u, int wr, int wc, int, int) const {
;     ...
;                     v4u w; w.x = cvt_pk(v[0], v[1]); w.y = cvt_pk(v[2], v[3]); w.z = cvt_pk(v[4], v[5]); w.w = cvt_pk(v[6], v[7]);
;                     *(v4u*)(Z + (size_t)row * NIN + c0) = w;
;                     if (wrA) {
;                         const int colA = c0 - (pn < 4 ? 512 : 1024);
;                         float* dst;
;                         if (samp) { const int rs = row - MP; dst = out + (pn < 4 ? O_AKS : O_AVS) + (size_t)l * 16 * 512 * 512 + ((size_t)((rs >> 6) * 512 + 448 + (rs & 63))) * 512 + colA; }
;                         else { const int sq = (row & 16383) - 15872; dst = out + (pn < 4 ? O_AKP : O_AVP) + (size_t)l * 2 * 512 * 512 + ((size_t)((row >> 14) * 512 + sq)) * 512 + colA; }
;                         *(f32x4*)dst = (f32x4){v[0], v[1], v[2], v[3]}; *(f32x4*)(dst + 4) = (f32x4){v[4], v[5], v[6], v[7]};
;                     }
;                     if (wrB && (samp || ai == 1)) {
;                         const int colB = c0 - (bj == 0 ? 2048 : 2176);
;                         float* dst;
;                         if (samp) { const int rs = row - MP; dst = out + (bj == 0 ? O_BKS : O_BVS) + (size_t)l * 16 * 128 * 128 + ((size_t)((rs >> 6) * 128 + 64 + (rs & 63))) * 128 + colB; }
;                         else { const int sq = (row & 16383) - 16256; dst = out + (bj == 0 ? O_BKP : O_BVP) + (size_t)l * 2 * 128 * 128 + ((size_t)((row >> 14) * 128 + sq)) * 128 + colB; }
;                         *(f32x4*)dst = (f32x4){v[0], v[1], v[2], v[3]}; *(f32x4*)(dst + 4) = (f32x4){v[4], v[5], v[6], v[7]};
;                     }
.LBB0_918:
	s_waitcnt lgkmcnt(7)
	v_add_u32_e32 v124, 0x80, v146
	s_waitcnt lgkmcnt(3)
	v_cvt_pk_bf16_f32 v120, v116, v117
	s_waitcnt lgkmcnt(2)
	v_cvt_pk_bf16_f32 v121, v118, v119
	v_cvt_pk_bf16_f32 v122, v112, v113
	v_cvt_pk_bf16_f32 v123, v114, v115
	global_store_dwordx4 v[162:163], v[120:123], off offset:256 sc1
	s_and_b64 vcc, exec, s[10:11]
	s_nop 0
	v_add_u32_e32 v120, s60, v124
	v_ashrrev_i32_e32 v121, 31, v120
	s_cbranch_vccnz .LBB0_920
	s_and_b64 s[60:61], s[6:7], exec
	s_cselect_b32 s36, s68, 0x200000
	v_lshl_add_u64 v[122:123], v[160:161], 0, s[36:37]
	v_lshl_add_u64 v[122:123], v[120:121], 2, v[122:123]
	global_store_dwordx4 v[122:123], v[116:119], off sc1
	global_store_dwordx4 v[122:123], v[112:115], off offset:16 sc1
.LBB0_920:
	s_and_b64 vcc, exec, s[16:17]
	s_cbranch_vccnz .LBB0_922
	v_lshl_add_u64 v[122:123], v[144:145], 2, v[164:165]
	v_lshl_add_u64 v[124:125], v[122:123], 0, s[46:47]
	v_add_co_u32_e32 v122, vcc, 0xcf80000, v122
	s_nop 1
	v_addc_co_u32_e32 v123, vcc, 0, v123, vcc
	global_store_dwordx4 v[122:123], v[116:119], off sc1
	global_store_dwordx4 v[124:125], v[112:115], off offset:16 sc1

;     __device__ __forceinline__ void operator()(AccRef acc, const pg8::Unit& u, int wr, int wc, int, int) const {
;     ...
;                 const int row = pm * 256 + ai * 128 + wr * 64 + m * 16 + fr;
;                 const float rstd = __builtin_amdgcn_rsqf(sq[ai][m] * (1.0f / DM) + EPS) * (isq ? QSCALE : 1.0f);
;                 const int pos = samp ? 2048 + ((row - MP) & 63) : (row & 16383);
; #pragma unroll
;                 for (int bj = 0; bj < 2; ++bj) {
;                     const int c0 = pn * 256 + bj * 128 + wc * 32 + 8 * fq;
;                     float v[8];
; #pragma unroll
;                     for (int j = 0; j < 4; ++j) { v[j] = acc[ai][bj][m][0][j] * rstd; v[4 + j] = acc[ai][bj][m][1][j] * rstd; }
;                     const bool ropet = (pn == 6 || pn == 7 || (pn == 8 && bj == 0)) && ((wc & 1) == 0);
;                     if (ropet) {
;                         float pv[8];
; #pragma unroll
;                         for (int j = 0; j < 8; ++j) pv[j] = __shfl_xor(v[j], 16);
;                         if (fq < 2) {
;                             const f32x4* cs = (const f32x4*)(rope + (size_t)pos * 16);
;                             const float sg = (fq == 0) ? -1.f : 1.f;
; #pragma unroll
;                             for (int jj = 0; jj < 4; ++jj) { const f32x4 t = cs[jj];
;                                 v[2 * jj] = v[2 * jj] * t[0] + sg * pv[2 * jj] * t[1];
;                                 v[2 * jj + 1] = v[2 * jj + 1] * t[2] + sg * pv[2 * jj + 1] * t[3]; }
;                         }
;                     }
;                     v4u w; w.x = cvt_pk(v[0], v[1]); w.y = cvt_pk(v[2], v[3]); w.z = cvt_pk(v[4], v[5]); w.w = cvt_pk(v[6], v[7]);
;                     *(v4u*)(Z + (size_t)row * NIN + c0) = w;
;                     if (wrA) {
;                         const int colA = c0 - (pn < 4 ? 512 : 1024);
;                         float* dst;
;                         if (samp) { const int rs = row - MP; dst = out + (pn < 4 ? O_AKS : O_AVS) + (size_t)l * 16 * 512 * 512 + ((size_t)((rs >> 6) * 512 + 448 + (rs & 63))) * 512 + colA; }
;                         else { const int sq = (row & 16383) - 15872; dst = out + (pn < 4 ? O_AKP : O_AVP) + (size_t)l * 2 * 512 * 512 + ((size_t)((row >> 14) * 512 + sq)) * 512 + colA; }
;                         *(f32x4*)dst = (f32x4){v[0], v[1], v[2], v[3]}; *(f32x4*)(dst + 4) = (f32x4){v[4], v[5], v[6], v[7]};
.LBB0_926:
	s_waitcnt lgkmcnt(5)
	v_add_u32_e32 v118, s49, v115
	s_waitcnt lgkmcnt(4)
	v_ashrrev_i32_e32 v119, 31, v118
	s_waitcnt lgkmcnt(0)
	v_or_b32_e32 v124, 16, v173
	v_lshlrev_b64 v[118:119], 11, v[118:119]
	v_lshl_add_u64 v[122:123], s[82:83], 0, v[118:119]
	v_or_b32_e32 v118, s3, v124
	v_ashrrev_i32_e32 v119, 31, v118
	v_mov_b64_e32 v[116:117], s[78:79]
	v_lshlrev_b64 v[118:119], 11, v[118:119]
	v_mad_i64_i32 v[116:117], s[60:61], v154, s63, v[116:117]
	v_lshl_add_u64 v[126:127], s[80:81], 0, v[118:119]
	v_lshl_add_u64 v[118:119], v[146:147], 1, v[116:117]
	s_and_b64 vcc, exec, s[10:11]
	v_cndmask_b32_e64 v117, v123, v127, s[6:7]
	v_cndmask_b32_e64 v116, v122, v126, s[6:7]
	v_cvt_pk_bf16_f32 v156, v108, v109
	v_cvt_pk_bf16_f32 v157, v110, v111
	v_cvt_pk_bf16_f32 v158, v104, v105
	v_cvt_pk_bf16_f32 v159, v106, v107
	global_store_dwordx4 v[118:119], v[156:159], off sc1
	s_cbranch_vccnz .LBB0_928
	s_and_b64 s[60:61], s[6:7], exec
	s_cselect_b32 s36, s68, 0x200000
	v_lshl_add_u64 v[122:123], v[116:117], 0, s[36:37]
	v_lshl_add_u64 v[122:123], v[148:149], 2, v[122:123]
	global_store_dwordx4 v[122:123], v[108:111], off sc1
	global_store_dwordx4 v[122:123], v[104:107], off offset:16 sc1
.LBB0_928:
	v_or_b32_e32 v122, s51, v124
	v_ashrrev_i32_e32 v123, 31, v122
	v_lshlrev_b64 v[122:123], 9, v[122:123]
	s_and_b64 vcc, exec, s[16:17]
	v_lshl_add_u64 v[122:123], s[58:59], 0, v[122:123]
	s_cbranch_vccnz .LBB0_930
	v_lshl_add_u64 v[126:127], v[144:145], 2, v[122:123]
	v_lshl_add_u64 v[156:157], v[126:127], 0, s[44:45]
	v_add_co_u32_e32 v126, vcc, 0xcd80000, v126
	s_nop 1
	v_addc_co_u32_e32 v127, vcc, 0, v127, vcc
	global_store_dwordx4 v[126:127], v[108:111], off sc1
	global_store_dwordx4 v[156:157], v[104:107], off offset:16 sc1

; __device__ __forceinline__ unsigned cvt_pk(float lo, float hi) { unsigned r; asm("v_cvt_pk_bf16_f32 %0, %1, %2" : "=v"(r) : "v"(lo), "v"(hi)); return r; }
;     __device__ __forceinline__ void operator()(AccRef acc, const pg8::Unit& u, int wr, int wc, int, int) const {
;     ...
;                     v4u w; w.x = cvt_pk(v[0], v[1]); w.y = cvt_pk(v[2], v[3]); w.z = cvt_pk(v[4], v[5]); w.w = cvt_pk(v[6], v[7]);
;                     *(v4u*)(Z + (size_t)row * NIN + c0) = w;
;                     if (wrA) {
;                         const int colA = c0 - (pn < 4 ? 512 : 1024);
;                         float* dst;
;                         if (samp) { const int rs = row - MP; dst = out + (pn < 4 ? O_AKS : O_AVS) + (size_t)l * 16 * 512 * 512 + ((size_t)((rs >> 6) * 512 + 448 + (rs & 63))) * 512 + colA; }
;                         else { const int sq = (row & 16383) - 15872; dst = out + (pn < 4 ? O_AKP : O_AVP) + (size_t)l * 2 * 512 * 512 + ((size_t)((row >> 14) * 512 + sq)) * 512 + colA; }
;                         *(f32x4*)dst = (f32x4){v[0], v[1], v[2], v[3]}; *(f32x4*)(dst + 4) = (f32x4){v[4], v[5], v[6], v[7]};
;                     }
;                     if (wrB && (samp || ai == 1)) {
;                         const int colB = c0 - (bj == 0 ? 2048 : 2176);
;                         float* dst;
;                         if (samp) { const int rs = row - MP; dst = out + (bj == 0 ? O_BKS : O_BVS) + (size_t)l * 16 * 128 * 128 + ((size_t)((rs >> 6) * 128 + 64 + (rs & 63))) * 128 + colB; }
;                         else { const int sq = (row & 16383) - 16256; dst = out + (bj == 0 ? O_BKP : O_BVP) + (size_t)l * 2 * 128 * 128 + ((size_t)((row >> 14) * 128 + sq)) * 128 + colB; }
;                         *(f32x4*)dst = (f32x4){v[0], v[1], v[2], v[3]}; *(f32x4*)(dst + 4) = (f32x4){v[4], v[5], v[6], v[7]};
;                     }
.LBB0_934:
	s_and_b64 vcc, exec, s[10:11]
	s_waitcnt lgkmcnt(3)
	v_cvt_pk_bf16_f32 v104, v100, v101
	s_waitcnt lgkmcnt(2)
	v_cvt_pk_bf16_f32 v105, v102, v103
	v_cvt_pk_bf16_f32 v106, v96, v97
	v_cvt_pk_bf16_f32 v107, v98, v99
	global_store_dwordx4 v[118:119], v[104:107], off offset:256 sc1
	s_cbranch_vccnz .LBB0_936
	s_and_b64 s[60:61], s[6:7], exec
	s_cselect_b32 s36, s68, 0x200000
	v_lshl_add_u64 v[104:105], v[116:117], 0, s[36:37]
	v_lshl_add_u64 v[104:105], v[120:121], 2, v[104:105]
	global_store_dwordx4 v[104:105], v[100:103], off sc1
	global_store_dwordx4 v[104:105], v[96:99], off offset:16 sc1
.LBB0_936:
	s_and_b64 vcc, exec, s[16:17]
	s_cbranch_vccnz .LBB0_938
	v_lshl_add_u64 v[104:105], v[144:145], 2, v[122:123]
	v_lshl_add_u64 v[106:107], v[104:105], 0, s[46:47]
	v_add_co_u32_e32 v104, vcc, 0xcf80000, v104
	s_nop 1
	v_addc_co_u32_e32 v105, vcc, 0, v105, vcc
	global_store_dwordx4 v[104:105], v[100:103], off sc1
	global_store_dwordx4 v[106:107], v[96:99], off offset:16 sc1

;     __device__ __forceinline__ void operator()(AccRef acc, const pg8::Unit& u, int wr, int wc, int, int) const {
;     ...
;                 const int row = pm * 256 + ai * 128 + wr * 64 + m * 16 + fr;
;                 const float rstd = __builtin_amdgcn_rsqf(sq[ai][m] * (1.0f / DM) + EPS) * (isq ? QSCALE : 1.0f);
;                 const int pos = samp ? 2048 + ((row - MP) & 63) : (row & 16383);
; #pragma unroll
;                 for (int bj = 0; bj < 2; ++bj) {
;                     const int c0 = pn * 256 + bj * 128 + wc * 32 + 8 * fq;
;                     float v[8];
; #pragma unroll
;                     for (int j = 0; j < 4; ++j) { v[j] = acc[ai][bj][m][0][j] * rstd; v[4 + j] = acc[ai][bj][m][1][j] * rstd; }
;                     const bool ropet = (pn == 6 || pn == 7 || (pn == 8 && bj == 0)) && ((wc & 1) == 0);
;                     if (ropet) {
;                         float pv[8];
; #pragma unroll
;                         for (int j = 0; j < 8; ++j) pv[j] = __shfl_xor(v[j], 16);
;                         if (fq < 2) {
;                             const f32x4* cs = (const f32x4*)(rope + (size_t)pos * 16);
;                             const float sg = (fq == 0) ? -1.f : 1.f;
; #pragma unroll
;                             for (int jj = 0; jj < 4; ++jj) { const f32x4 t = cs[jj];
;                                 v[2 * jj] = v[2 * jj] * t[0] + sg * pv[2 * jj] * t[1];
;                                 v[2 * jj + 1] = v[2 * jj + 1] * t[2] + sg * pv[2 * jj + 1] * t[3]; }
;                         }
;                     }
;                     v4u w; w.x = cvt_pk(v[0], v[1]); w.y = cvt_pk(v[2], v[3]); w.z = cvt_pk(v[4], v[5]); w.w = cvt_pk(v[6], v[7]);
;                     *(v4u*)(Z + (size_t)row * NIN + c0) = w;
;                     if (wrA) {
;                         const int colA = c0 - (pn < 4 ? 512 : 1024);
;                         float* dst;
;                         if (samp) { const int rs = row - MP; dst = out + (pn < 4 ? O_AKS : O_AVS) + (size_t)l * 16 * 512 * 512 + ((size_t)((rs >> 6) * 512 + 448 + (rs & 63))) * 512 + colA; }
;                         else { const int sq = (row & 16383) - 15872; dst = out + (pn < 4 ? O_AKP : O_AVP) + (size_t)l * 2 * 512 * 512 + ((size_t)((row >> 14) * 512 + sq)) * 512 + colA; }
;                         *(f32x4*)dst = (f32x4){v[0], v[1], v[2], v[3]}; *(f32x4*)(dst + 4) = (f32x4){v[4], v[5], v[6], v[7]};
.LBB0_942:
	s_waitcnt lgkmcnt(5)
	v_add_u32_e32 v102, s49, v99
	s_waitcnt lgkmcnt(4)
	v_ashrrev_i32_e32 v103, 31, v102
	s_waitcnt lgkmcnt(0)
	v_or_b32_e32 v106, 32, v173
	v_lshlrev_b64 v[102:103], 11, v[102:103]
	v_lshl_add_u64 v[104:105], s[82:83], 0, v[102:103]
	v_or_b32_e32 v102, s3, v106
	v_ashrrev_i32_e32 v103, 31, v102
	v_mov_b64_e32 v[100:101], s[78:79]
	v_lshlrev_b64 v[102:103], 11, v[102:103]
	v_mad_i64_i32 v[100:101], s[60:61], v152, s63, v[100:101]
	v_lshl_add_u64 v[112:113], s[80:81], 0, v[102:103]
	v_lshl_add_u64 v[102:103], v[146:147], 1, v[100:101]
	s_and_b64 vcc, exec, s[10:11]
	v_cndmask_b32_e64 v101, v105, v113, s[6:7]
	v_cndmask_b32_e64 v100, v104, v112, s[6:7]
	v_cvt_pk_bf16_f32 v108, v92, v93
	v_cvt_pk_bf16_f32 v109, v94, v95
	v_cvt_pk_bf16_f32 v110, v88, v89
	v_cvt_pk_bf16_f32 v111, v90, v91
	global_store_dwordx4 v[102:103], v[108:111], off sc1
	s_cbranch_vccnz .LBB0_944
	s_and_b64 s[60:61], s[6:7], exec
	s_cselect_b32 s36, s68, 0x200000
	v_lshl_add_u64 v[104:105], v[100:101], 0, s[36:37]
	v_lshl_add_u64 v[104:105], v[148:149], 2, v[104:105]
	global_store_dwordx4 v[104:105], v[92:95], off sc1
	global_store_dwordx4 v[104:105], v[88:91], off offset:16 sc1
.LBB0_944:
	v_or_b32_e32 v104, s51, v106
	v_ashrrev_i32_e32 v105, 31, v104
	v_lshlrev_b64 v[104:105], 9, v[104:105]
	s_and_b64 vcc, exec, s[16:17]
	v_lshl_add_u64 v[104:105], s[58:59], 0, v[104:105]
	s_cbranch_vccnz .LBB0_946
	v_lshl_add_u64 v[108:109], v[144:145], 2, v[104:105]
	v_lshl_add_u64 v[110:111], v[108:109], 0, s[44:45]
	v_add_co_u32_e32 v108, vcc, 0xcd80000, v108
	s_nop 1
	v_addc_co_u32_e32 v109, vcc, 0, v109, vcc
	global_store_dwordx4 v[108:109], v[92:95], off sc1
	global_store_dwordx4 v[110:111], v[88:91], off offset:16 sc1

; __device__ __forceinline__ unsigned cvt_pk(float lo, float hi) { unsigned r; asm("v_cvt_pk_bf16_f32 %0, %1, %2" : "=v"(r) : "v"(lo), "v"(hi)); return r; }
;     __device__ __forceinline__ void operator()(AccRef acc, const pg8::Unit& u, int wr, int wc, int, int) const {
;     ...
;                     v4u w; w.x = cvt_pk(v[0], v[1]); w.y = cvt_pk(v[2], v[3]); w.z = cvt_pk(v[4], v[5]); w.w = cvt_pk(v[6], v[7]);
;                     *(v4u*)(Z + (size_t)row * NIN + c0) = w;
;                     if (wrA) {
;                         const int colA = c0 - (pn < 4 ? 512 : 1024);
;                         float* dst;
;                         if (samp) { const int rs = row - MP; dst = out + (pn < 4 ? O_AKS : O_AVS) + (size_t)l * 16 * 512 * 512 + ((size_t)((rs >> 6) * 512 + 448 + (rs & 63))) * 512 + colA; }
;                         else { const int sq = (row & 16383) - 15872; dst = out + (pn < 4 ? O_AKP : O_AVP) + (size_t)l * 2 * 512 * 512 + ((size_t)((row >> 14) * 512 + sq)) * 512 + colA; }
;                         *(f32x4*)dst = (f32x4){v[0], v[1], v[2], v[3]}; *(f32x4*)(dst + 4) = (f32x4){v[4], v[5], v[6], v[7]};
;                     }
;                     if (wrB && (samp || ai == 1)) {
;                         const int colB = c0 - (bj == 0 ? 2048 : 2176);
;                         float* dst;
;                         if (samp) { const int rs = row - MP; dst = out + (bj == 0 ? O_BKS : O_BVS) + (size_t)l * 16 * 128 * 128 + ((size_t)((rs >> 6) * 128 + 64 + (rs & 63))) * 128 + colB; }
;                         else { const int sq = (row & 16383) - 16256; dst = out + (bj == 0 ? O_BKP : O_BVP) + (size_t)l * 2 * 128 * 128 + ((size_t)((row >> 14) * 128 + sq)) * 128 + colB; }
;                         *(f32x4*)dst = (f32x4){v[0], v[1], v[2], v[3]}; *(f32x4*)(dst + 4) = (f32x4){v[4], v[5], v[6], v[7]};
;                     }
.LBB0_950:
	s_and_b64 vcc, exec, s[10:11]
	s_waitcnt lgkmcnt(3)
	v_cvt_pk_bf16_f32 v88, v84, v85
	s_waitcnt lgkmcnt(2)
	v_cvt_pk_bf16_f32 v89, v86, v87
	v_cvt_pk_bf16_f32 v90, v80, v81
	v_cvt_pk_bf16_f32 v91, v82, v83
	global_store_dwordx4 v[102:103], v[88:91], off offset:256 sc1
	s_cbranch_vccnz .LBB0_952
	s_and_b64 s[60:61], s[6:7], exec
	s_cselect_b32 s36, s68, 0x200000
	v_lshl_add_u64 v[88:89], v[100:101], 0, s[36:37]
	v_lshl_add_u64 v[88:89], v[120:121], 2, v[88:89]
	global_store_dwordx4 v[88:89], v[84:87], off sc1
	global_store_dwordx4 v[88:89], v[80:83], off offset:16 sc1
.LBB0_952:
	s_and_b64 vcc, exec, s[16:17]
	s_cbranch_vccnz .LBB0_954
	v_lshl_add_u64 v[88:89], v[144:145], 2, v[104:105]
	v_lshl_add_u64 v[90:91], v[88:89], 0, s[46:47]
	v_add_co_u32_e32 v88, vcc, 0xcf80000, v88
	s_nop 1
	v_addc_co_u32_e32 v89, vcc, 0, v89, vcc
	global_store_dwordx4 v[88:89], v[84:87], off sc1
	global_store_dwordx4 v[90:91], v[80:83], off offset:16 sc1

;     __device__ __forceinline__ void operator()(AccRef acc, const pg8::Unit& u, int wr, int wc, int, int) const {
;     ...
;                 const int row = pm * 256 + ai * 128 + wr * 64 + m * 16 + fr;
;                 const float rstd = __builtin_amdgcn_rsqf(sq[ai][m] * (1.0f / DM) + EPS) * (isq ? QSCALE : 1.0f);
;                 const int pos = samp ? 2048 + ((row - MP) & 63) : (row & 16383);
; #pragma unroll
;                 for (int bj = 0; bj < 2; ++bj) {
;                     const int c0 = pn * 256 + bj * 128 + wc * 32 + 8 * fq;
;                     float v[8];
; #pragma unroll
;                     for (int j = 0; j < 4; ++j) { v[j] = acc[ai][bj][m][0][j] * rstd; v[4 + j] = acc[ai][bj][m][1][j] * rstd; }
;                     const bool ropet = (pn == 6 || pn == 7 || (pn == 8 && bj == 0)) && ((wc & 1) == 0);
;                     if (ropet) {
;                         float pv[8];
; #pragma unroll
;                         for (int j = 0; j < 8; ++j) pv[j] = __shfl_xor(v[j], 16);
;                         if (fq < 2) {
;                             const f32x4* cs = (const f32x4*)(rope + (size_t)pos * 16);
;                             const float sg = (fq == 0) ? -1.f : 1.f;
; #pragma unroll
;                             for (int jj = 0; jj < 4; ++jj) { const f32x4 t = cs[jj];
;                                 v[2 * jj] = v[2 * jj] * t[0] + sg * pv[2 * jj] * t[1];
;                                 v[2 * jj + 1] = v[2 * jj + 1] * t[2] + sg * pv[2 * jj + 1] * t[3]; }
;                         }
;                     }
;                     v4u w; w.x = cvt_pk(v[0], v[1]); w.y = cvt_pk(v[2], v[3]); w.z = cvt_pk(v[4], v[5]); w.w = cvt_pk(v[6], v[7]);
;                     *(v4u*)(Z + (size_t)row * NIN + c0) = w;
;                     if (wrA) {
;                         const int colA = c0 - (pn < 4 ? 512 : 1024);
;                         float* dst;
;                         if (samp) { const int rs = row - MP; dst = out + (pn < 4 ? O_AKS : O_AVS) + (size_t)l * 16 * 512 * 512 + ((size_t)((rs >> 6) * 512 + 448 + (rs & 63))) * 512 + colA; }
;                         else { const int sq = (row & 16383) - 15872; dst = out + (pn < 4 ? O_AKP : O_AVP) + (size_t)l * 2 * 512 * 512 + ((size_t)((row >> 14) * 512 + sq)) * 512 + colA; }
;                         *(f32x4*)dst = (f32x4){v[0], v[1], v[2], v[3]}; *(f32x4*)(dst + 4) = (f32x4){v[4], v[5], v[6], v[7]};
.LBB0_958:
	s_waitcnt lgkmcnt(5)
	v_add_u32_e32 v86, s49, v83
	s_waitcnt lgkmcnt(4)
	v_ashrrev_i32_e32 v87, 31, v86
	s_waitcnt lgkmcnt(0)
	v_or_b32_e32 v90, 48, v173
	v_lshlrev_b64 v[86:87], 11, v[86:87]
	v_lshl_add_u64 v[88:89], s[82:83], 0, v[86:87]
	v_or_b32_e32 v86, s3, v90
	v_ashrrev_i32_e32 v87, 31, v86
	v_mov_b64_e32 v[84:85], s[78:79]
	v_lshlrev_b64 v[86:87], 11, v[86:87]
	v_mad_i64_i32 v[84:85], s[60:61], v150, s63, v[84:85]
	v_lshl_add_u64 v[96:97], s[80:81], 0, v[86:87]
	v_lshl_add_u64 v[86:87], v[146:147], 1, v[84:85]
	s_and_b64 vcc, exec, s[10:11]
	v_cndmask_b32_e64 v85, v89, v97, s[6:7]
	v_cndmask_b32_e64 v84, v88, v96, s[6:7]
	v_cvt_pk_bf16_f32 v92, v76, v77
	v_cvt_pk_bf16_f32 v93, v78, v79
	v_cvt_pk_bf16_f32 v94, v72, v73
	v_cvt_pk_bf16_f32 v95, v74, v75
	global_store_dwordx4 v[86:87], v[92:95], off sc1
	s_cbranch_vccnz .LBB0_960
	s_and_b64 s[60:61], s[6:7], exec
	s_cselect_b32 s36, s68, 0x200000
	v_lshl_add_u64 v[88:89], v[84:85], 0, s[36:37]
	v_lshl_add_u64 v[88:89], v[148:149], 2, v[88:89]
	global_store_dwordx4 v[88:89], v[76:79], off sc1
	global_store_dwordx4 v[88:89], v[72:75], off offset:16 sc1
.LBB0_960:
	v_or_b32_e32 v88, s51, v90
	v_ashrrev_i32_e32 v89, 31, v88
	v_lshlrev_b64 v[88:89], 9, v[88:89]
	s_and_b64 vcc, exec, s[16:17]
	v_lshl_add_u64 v[88:89], s[58:59], 0, v[88:89]
	s_cbranch_vccnz .LBB0_962
	v_lshl_add_u64 v[92:93], v[144:145], 2, v[88:89]
	v_lshl_add_u64 v[94:95], v[92:93], 0, s[44:45]
	v_add_co_u32_e32 v92, vcc, 0xcd80000, v92
	s_nop 1
	v_addc_co_u32_e32 v93, vcc, 0, v93, vcc
	global_store_dwordx4 v[92:93], v[76:79], off sc1
	global_store_dwordx4 v[94:95], v[72:75], off offset:16 sc1

; __device__ __forceinline__ unsigned cvt_pk(float lo, float hi) { unsigned r; asm("v_cvt_pk_bf16_f32 %0, %1, %2" : "=v"(r) : "v"(lo), "v"(hi)); return r; }
;     __device__ __forceinline__ void operator()(AccRef acc, const pg8::Unit& u, int wr, int wc, int, int) const {
;     ...
;                     v4u w; w.x = cvt_pk(v[0], v[1]); w.y = cvt_pk(v[2], v[3]); w.z = cvt_pk(v[4], v[5]); w.w = cvt_pk(v[6], v[7]);
;                     *(v4u*)(Z + (size_t)row * NIN + c0) = w;
;                     if (wrA) {
;                         const int colA = c0 - (pn < 4 ? 512 : 1024);
;                         float* dst;
;                         if (samp) { const int rs = row - MP; dst = out + (pn < 4 ? O_AKS : O_AVS) + (size_t)l * 16 * 512 * 512 + ((size_t)((rs >> 6) * 512 + 448 + (rs & 63))) * 512 + colA; }
;                         else { const int sq = (row & 16383) - 15872; dst = out + (pn < 4 ? O_AKP : O_AVP) + (size_t)l * 2 * 512 * 512 + ((size_t)((row >> 14) * 512 + sq)) * 512 + colA; }
;                         *(f32x4*)dst = (f32x4){v[0], v[1], v[2], v[3]}; *(f32x4*)(dst + 4) = (f32x4){v[4], v[5], v[6], v[7]};
;                     }
;                     if (wrB && (samp || ai == 1)) {
;                         const int colB = c0 - (bj == 0 ? 2048 : 2176);
;                         float* dst;
;                         if (samp) { const int rs = row - MP; dst = out + (bj == 0 ? O_BKS : O_BVS) + (size_t)l * 16 * 128 * 128 + ((size_t)((rs >> 6) * 128 + 64 + (rs & 63))) * 128 + colB; }
;                         else { const int sq = (row & 16383) - 16256; dst = out + (bj == 0 ? O_BKP : O_BVP) + (size_t)l * 2 * 128 * 128 + ((size_t)((row >> 14) * 128 + sq)) * 128 + colB; }
;                         *(f32x4*)dst = (f32x4){v[0], v[1], v[2], v[3]}; *(f32x4*)(dst + 4) = (f32x4){v[4], v[5], v[6], v[7]};
;                     }
.LBB0_966:
	s_and_b64 vcc, exec, s[10:11]
	s_waitcnt lgkmcnt(3)
	v_cvt_pk_bf16_f32 v72, v68, v69
	s_waitcnt lgkmcnt(2)
	v_cvt_pk_bf16_f32 v73, v70, v71
	v_cvt_pk_bf16_f32 v74, v64, v65
	v_cvt_pk_bf16_f32 v75, v66, v67
	global_store_dwordx4 v[86:87], v[72:75], off offset:256 sc1
	s_cbranch_vccnz .LBB0_968
	s_and_b64 s[60:61], s[6:7], exec
	s_cselect_b32 s36, s68, 0x200000
	v_lshl_add_u64 v[72:73], v[84:85], 0, s[36:37]
	v_lshl_add_u64 v[72:73], v[120:121], 2, v[72:73]
	global_store_dwordx4 v[72:73], v[68:71], off sc1
	global_store_dwordx4 v[72:73], v[64:67], off offset:16 sc1
.LBB0_968:
	s_and_b64 vcc, exec, s[16:17]
	s_cbranch_vccnz .LBB0_970
	v_lshl_add_u64 v[72:73], v[144:145], 2, v[88:89]
	v_lshl_add_u64 v[74:75], v[72:73], 0, s[46:47]
	v_add_co_u32_e32 v72, vcc, 0xcf80000, v72
	s_nop 1
	v_addc_co_u32_e32 v73, vcc, 0, v73, vcc
	global_store_dwordx4 v[72:73], v[68:71], off sc1
	global_store_dwordx4 v[74:75], v[64:67], off offset:16 sc1

;     __device__ __forceinline__ void operator()(AccRef acc, const pg8::Unit& u, int wr, int wc, int, int) const {
;     ...
;                 const int row = pm * 256 + ai * 128 + wr * 64 + m * 16 + fr;
;                 const float rstd = __builtin_amdgcn_rsqf(sq[ai][m] * (1.0f / DM) + EPS) * (isq ? QSCALE : 1.0f);
;                 const int pos = samp ? 2048 + ((row - MP) & 63) : (row & 16383);
; #pragma unroll
;                 for (int bj = 0; bj < 2; ++bj) {
;                     const int c0 = pn * 256 + bj * 128 + wc * 32 + 8 * fq;
;                     float v[8];
; #pragma unroll
;                     for (int j = 0; j < 4; ++j) { v[j] = acc[ai][bj][m][0][j] * rstd; v[4 + j] = acc[ai][bj][m][1][j] * rstd; }
;                     const bool ropet = (pn == 6 || pn == 7 || (pn == 8 && bj == 0)) && ((wc & 1) == 0);
;                     if (ropet) {
;                         float pv[8];
; #pragma unroll
;                         for (int j = 0; j < 8; ++j) pv[j] = __shfl_xor(v[j], 16);
;                         if (fq < 2) {
;                             const f32x4* cs = (const f32x4*)(rope + (size_t)pos * 16);
;                             const float sg = (fq == 0) ? -1.f : 1.f;
; #pragma unroll
;                             for (int jj = 0; jj < 4; ++jj) { const f32x4 t = cs[jj];
;                                 v[2 * jj] = v[2 * jj] * t[0] + sg * pv[2 * jj] * t[1];
;                                 v[2 * jj + 1] = v[2 * jj + 1] * t[2] + sg * pv[2 * jj + 1] * t[3]; }
;                         }
;                     }
;                     v4u w; w.x = cvt_pk(v[0], v[1]); w.y = cvt_pk(v[2], v[3]); w.z = cvt_pk(v[4], v[5]); w.w = cvt_pk(v[6], v[7]);
;                     *(v4u*)(Z + (size_t)row * NIN + c0) = w;
;                     if (wrA) {
;                         const int colA = c0 - (pn < 4 ? 512 : 1024);
;                         float* dst;
;                         if (samp) { const int rs = row - MP; dst = out + (pn < 4 ? O_AKS : O_AVS) + (size_t)l * 16 * 512 * 512 + ((size_t)((rs >> 6) * 512 + 448 + (rs & 63))) * 512 + colA; }
;                         else { const int sq = (row & 16383) - 15872; dst = out + (pn < 4 ? O_AKP : O_AVP) + (size_t)l * 2 * 512 * 512 + ((size_t)((row >> 14) * 512 + sq)) * 512 + colA; }
;                         *(f32x4*)dst = (f32x4){v[0], v[1], v[2], v[3]}; *(f32x4*)(dst + 4) = (f32x4){v[4], v[5], v[6], v[7]};
.LBB0_974:
	s_ashr_i32 s2, s49, 5
	s_and_b32 s3, s2, 0xfffffe00
	s_addk_i32 s3, 0xc200
	s_waitcnt lgkmcnt(5)
	v_add_u32_e32 v70, s3, v67
	s_lshl_b32 s2, s49, 3
	s_waitcnt lgkmcnt(4)
	v_ashrrev_i32_e32 v71, 31, v70
	s_add_i32 s2, s2, 0xfffc01c0
	v_lshlrev_b64 v[70:71], 11, v[70:71]
	v_lshl_add_u64 v[72:73], s[82:83], 0, v[70:71]
	v_or_b32_e32 v70, s2, v173
	v_ashrrev_i32_e32 v71, 31, v70
	s_waitcnt lgkmcnt(0)
	v_or_b32_e32 v74, s49, v173
	v_mov_b64_e32 v[68:69], s[78:79]
	v_lshlrev_b64 v[70:71], 11, v[70:71]
	v_mad_i64_i32 v[68:69], s[16:17], v74, s63, v[68:69]
	v_lshl_add_u64 v[80:81], s[80:81], 0, v[70:71]
	v_lshl_add_u64 v[70:71], v[146:147], 1, v[68:69]
	s_and_b64 vcc, exec, s[10:11]
	v_cndmask_b32_e64 v69, v73, v81, s[6:7]
	v_cndmask_b32_e64 v68, v72, v80, s[6:7]
	v_cvt_pk_bf16_f32 v76, v60, v61
	v_cvt_pk_bf16_f32 v77, v62, v63
	v_cvt_pk_bf16_f32 v78, v56, v57
	v_cvt_pk_bf16_f32 v79, v58, v59
	global_store_dwordx4 v[70:71], v[76:79], off sc1
	s_cbranch_vccnz .LBB0_976
	s_and_b64 s[16:17], s[6:7], exec
	s_cselect_b32 s36, s68, 0x200000
	v_lshl_add_u64 v[72:73], v[68:69], 0, s[36:37]
	v_lshl_add_u64 v[72:73], v[148:149], 2, v[72:73]
	global_store_dwordx4 v[72:73], v[60:63], off sc1
	global_store_dwordx4 v[72:73], v[56:59], off offset:16 sc1
.LBB0_976:
	s_and_b32 s16, s66, 63
	s_cmp_eq_u32 s16, 63
	s_cselect_b64 s[16:17], -1, 0
	s_or_b64 s[16:17], s[6:7], s[16:17]
	s_and_b64 s[30:31], s[30:31], s[16:17]
	s_ashr_i32 s16, s49, 7
	s_and_b32 s51, s16, 0xffffff80
	s_lshl_b32 s49, s49, 1
	s_addk_i32 s51, 0xc080
	s_add_i32 s49, s49, 0xffff0040
	v_add_u32_e32 v72, s51, v67
	v_or_b32_e32 v76, s49, v173
	v_ashrrev_i32_e32 v73, 31, v72
	v_ashrrev_i32_e32 v77, 31, v76
	v_lshlrev_b64 v[72:73], 9, v[72:73]
	v_lshlrev_b64 v[76:77], 9, v[76:77]
	v_cndmask_b32_e64 v67, 0, 1, s[30:31]
	v_cmp_ne_u32_e64 s[16:17], 1, v67
	s_andn2_b64 vcc, exec, s[30:31]
	v_cndmask_b32_e64 v73, v73, v77, s[6:7]
	v_cndmask_b32_e64 v72, v72, v76, s[6:7]
	s_cbranch_vccnz .LBB0_978
	s_and_b64 s[30:31], s[6:7], exec
	s_cselect_b32 s30, s70, 0x8c00000
	s_add_u32 s36, s58, s30
	s_addc_u32 s60, s59, 0
	s_and_b64 s[30:31], s[6:7], exec
	s_cselect_b32 s30, s71, 0x20000
	s_add_u32 s30, s36, s30
	s_addc_u32 s31, s60, 0
	v_lshl_add_u64 v[76:77], s[30:31], 0, v[72:73]
	v_lshl_add_u64 v[76:77], v[144:145], 2, v[76:77]
	global_store_dwordx4 v[76:77], v[60:63], off sc1
	global_store_dwordx4 v[76:77], v[56:59], off offset:16 sc1

; __device__ __forceinline__ unsigned cvt_pk(float lo, float hi) { unsigned r; asm("v_cvt_pk_bf16_f32 %0, %1, %2" : "=v"(r) : "v"(lo), "v"(hi)); return r; }
;     __device__ __forceinline__ void operator()(AccRef acc, const pg8::Unit& u, int wr, int wc, int, int) const {
;     ...
;                     v4u w; w.x = cvt_pk(v[0], v[1]); w.y = cvt_pk(v[2], v[3]); w.z = cvt_pk(v[4], v[5]); w.w = cvt_pk(v[6], v[7]);
;                     *(v4u*)(Z + (size_t)row * NIN + c0) = w;
;                     if (wrA) {
;                         const int colA = c0 - (pn < 4 ? 512 : 1024);
;                         float* dst;
;                         if (samp) { const int rs = row - MP; dst = out + (pn < 4 ? O_AKS : O_AVS) + (size_t)l * 16 * 512 * 512 + ((size_t)((rs >> 6) * 512 + 448 + (rs & 63))) * 512 + colA; }
;                         else { const int sq = (row & 16383) - 15872; dst = out + (pn < 4 ? O_AKP : O_AVP) + (size_t)l * 2 * 512 * 512 + ((size_t)((row >> 14) * 512 + sq)) * 512 + colA; }
;                         *(f32x4*)dst = (f32x4){v[0], v[1], v[2], v[3]}; *(f32x4*)(dst + 4) = (f32x4){v[4], v[5], v[6], v[7]};
;                     }
;                     if (wrB && (samp || ai == 1)) {
;                         const int colB = c0 - (bj == 0 ? 2048 : 2176);
;                         float* dst;
;                         if (samp) { const int rs = row - MP; dst = out + (bj == 0 ? O_BKS : O_BVS) + (size_t)l * 16 * 128 * 128 + ((size_t)((rs >> 6) * 128 + 64 + (rs & 63))) * 128 + colB; }
;                         else { const int sq = (row & 16383) - 16256; dst = out + (bj == 0 ? O_BKP : O_BVP) + (size_t)l * 2 * 128 * 128 + ((size_t)((row >> 14) * 128 + sq)) * 128 + colB; }
;                         *(f32x4*)dst = (f32x4){v[0], v[1], v[2], v[3]}; *(f32x4*)(dst + 4) = (f32x4){v[4], v[5], v[6], v[7]};
;                     }
.LBB0_982:
	s_and_b64 vcc, exec, s[10:11]
	s_waitcnt lgkmcnt(3)
	v_cvt_pk_bf16_f32 v56, v52, v53
	s_waitcnt lgkmcnt(2)
	v_cvt_pk_bf16_f32 v57, v54, v55
	v_cvt_pk_bf16_f32 v58, v48, v49
	v_cvt_pk_bf16_f32 v59, v50, v51
	global_store_dwordx4 v[70:71], v[56:59], off offset:256 sc1
	s_cbranch_vccnz .LBB0_984
	s_and_b64 s[30:31], s[6:7], exec
	s_cselect_b32 s36, s68, 0x200000
	v_lshl_add_u64 v[56:57], v[68:69], 0, s[36:37]
	v_lshl_add_u64 v[56:57], v[120:121], 2, v[56:57]
	global_store_dwordx4 v[56:57], v[52:55], off sc1
	global_store_dwordx4 v[56:57], v[48:51], off offset:16 sc1
.LBB0_984:
	s_and_b64 vcc, exec, s[16:17]
	s_cbranch_vccnz .LBB0_986
	s_and_b64 s[30:31], s[6:7], exec
	s_cselect_b32 s30, s0, 0x8c40000
	s_add_u32 s36, s58, s30
	s_addc_u32 s60, s59, 0
	s_and_b64 s[30:31], s[6:7], exec
	s_cselect_b32 s30, s71, 0x20000
	s_add_u32 s30, s36, s30
	s_addc_u32 s31, s60, 0
	v_lshl_add_u64 v[56:57], s[30:31], 0, v[72:73]
	v_lshl_add_u64 v[56:57], v[144:145], 2, v[56:57]
	global_store_dwordx4 v[56:57], v[52:55], off sc1
	global_store_dwordx4 v[56:57], v[48:51], off offset:16 sc1

;     __device__ __forceinline__ void operator()(AccRef acc, const pg8::Unit& u, int wr, int wc, int, int) const {
;     ...
;                 const int row = pm * 256 + ai * 128 + wr * 64 + m * 16 + fr;
;                 const float rstd = __builtin_amdgcn_rsqf(sq[ai][m] * (1.0f / DM) + EPS) * (isq ? QSCALE : 1.0f);
;                 const int pos = samp ? 2048 + ((row - MP) & 63) : (row & 16383);
; #pragma unroll
;                 for (int bj = 0; bj < 2; ++bj) {
;                     const int c0 = pn * 256 + bj * 128 + wc * 32 + 8 * fq;
;                     float v[8];
; #pragma unroll
;                     for (int j = 0; j < 4; ++j) { v[j] = acc[ai][bj][m][0][j] * rstd; v[4 + j] = acc[ai][bj][m][1][j] * rstd; }
;                     const bool ropet = (pn == 6 || pn == 7 || (pn == 8 && bj == 0)) && ((wc & 1) == 0);
;                     if (ropet) {
;                         float pv[8];
; #pragma unroll
;                         for (int j = 0; j < 8; ++j) pv[j] = __shfl_xor(v[j], 16);
;                         if (fq < 2) {
;                             const f32x4* cs = (const f32x4*)(rope + (size_t)pos * 16);
;                             const float sg = (fq == 0) ? -1.f : 1.f;
; #pragma unroll
;                             for (int jj = 0; jj < 4; ++jj) { const f32x4 t = cs[jj];
;                                 v[2 * jj] = v[2 * jj] * t[0] + sg * pv[2 * jj] * t[1];
;                                 v[2 * jj + 1] = v[2 * jj + 1] * t[2] + sg * pv[2 * jj + 1] * t[3]; }
;                         }
;                     }
;                     v4u w; w.x = cvt_pk(v[0], v[1]); w.y = cvt_pk(v[2], v[3]); w.z = cvt_pk(v[4], v[5]); w.w = cvt_pk(v[6], v[7]);
;                     *(v4u*)(Z + (size_t)row * NIN + c0) = w;
;                     if (wrA) {
;                         const int colA = c0 - (pn < 4 ? 512 : 1024);
;                         float* dst;
;                         if (samp) { const int rs = row - MP; dst = out + (pn < 4 ? O_AKS : O_AVS) + (size_t)l * 16 * 512 * 512 + ((size_t)((rs >> 6) * 512 + 448 + (rs & 63))) * 512 + colA; }
;                         else { const int sq = (row & 16383) - 15872; dst = out + (pn < 4 ? O_AKP : O_AVP) + (size_t)l * 2 * 512 * 512 + ((size_t)((row >> 14) * 512 + sq)) * 512 + colA; }
;                         *(f32x4*)dst = (f32x4){v[0], v[1], v[2], v[3]}; *(f32x4*)(dst + 4) = (f32x4){v[4], v[5], v[6], v[7]};
.LBB0_990:
	s_waitcnt lgkmcnt(5)
	v_or_b32_e32 v54, 16, v74
	s_waitcnt lgkmcnt(2)
	v_mov_b64_e32 v[52:53], s[78:79]
	v_mad_i64_i32 v[56:57], s[30:31], v54, s63, v[52:53]
	v_add_u32_e32 v52, s3, v51
	v_ashrrev_i32_e32 v53, 31, v52
	v_lshlrev_b64 v[52:53], 11, v[52:53]
	s_waitcnt lgkmcnt(0)
	v_lshl_add_u64 v[58:59], s[82:83], 0, v[52:53]
	v_or_b32_e32 v52, s2, v124
	v_ashrrev_i32_e32 v53, 31, v52
	v_lshlrev_b64 v[52:53], 11, v[52:53]
	v_lshl_add_u64 v[60:61], s[80:81], 0, v[52:53]
	v_cvt_pk_bf16_f32 v52, v44, v45
	v_cvt_pk_bf16_f32 v53, v46, v47
	v_lshl_add_u64 v[56:57], v[146:147], 1, v[56:57]
	v_cvt_pk_bf16_f32 v54, v40, v41
	v_cvt_pk_bf16_f32 v55, v42, v43
	global_store_dwordx4 v[56:57], v[52:55], off sc1
	s_and_b64 vcc, exec, s[10:11]
	s_nop 0
	v_cndmask_b32_e64 v53, v59, v61, s[6:7]
	v_cndmask_b32_e64 v52, v58, v60, s[6:7]
	s_cbranch_vccnz .LBB0_992
	s_and_b64 s[30:31], s[6:7], exec
	s_cselect_b32 s36, s68, 0x200000
	v_lshl_add_u64 v[54:55], v[52:53], 0, s[36:37]
	v_lshl_add_u64 v[54:55], v[148:149], 2, v[54:55]
	global_store_dwordx4 v[54:55], v[44:47], off sc1
	global_store_dwordx4 v[54:55], v[40:43], off offset:16 sc1
.LBB0_992:
	v_add_u32_e32 v54, s51, v51
	v_or_b32_e32 v58, s49, v124
	v_ashrrev_i32_e32 v55, 31, v54
	v_ashrrev_i32_e32 v59, 31, v58
	v_lshlrev_b64 v[54:55], 9, v[54:55]
	v_lshlrev_b64 v[58:59], 9, v[58:59]
	s_and_b64 vcc, exec, s[16:17]
	v_cndmask_b32_e64 v55, v55, v59, s[6:7]
	v_cndmask_b32_e64 v54, v54, v58, s[6:7]
	s_cbranch_vccnz .LBB0_994
	s_and_b64 s[30:31], s[6:7], exec
	s_cselect_b32 s30, s70, 0x8c00000
	s_add_u32 s36, s58, s30
	s_addc_u32 s60, s59, 0
	s_and_b64 s[30:31], s[6:7], exec
	s_cselect_b32 s30, s71, 0x20000
	s_add_u32 s30, s36, s30
	s_addc_u32 s31, s60, 0
	v_lshl_add_u64 v[58:59], s[30:31], 0, v[54:55]
	v_lshl_add_u64 v[58:59], v[144:145], 2, v[58:59]
	global_store_dwordx4 v[58:59], v[44:47], off sc1
	global_store_dwordx4 v[58:59], v[40:43], off offset:16 sc1

; __device__ __forceinline__ unsigned cvt_pk(float lo, float hi) { unsigned r; asm("v_cvt_pk_bf16_f32 %0, %1, %2" : "=v"(r) : "v"(lo), "v"(hi)); return r; }
;     __device__ __forceinline__ void operator()(AccRef acc, const pg8::Unit& u, int wr, int wc, int, int) const {
;     ...
;                     v4u w; w.x = cvt_pk(v[0], v[1]); w.y = cvt_pk(v[2], v[3]); w.z = cvt_pk(v[4], v[5]); w.w = cvt_pk(v[6], v[7]);
;                     *(v4u*)(Z + (size_t)row * NIN + c0) = w;
;                     if (wrA) {
;                         const int colA = c0 - (pn < 4 ? 512 : 1024);
;                         float* dst;
;                         if (samp) { const int rs = row - MP; dst = out + (pn < 4 ? O_AKS : O_AVS) + (size_t)l * 16 * 512 * 512 + ((size_t)((rs >> 6) * 512 + 448 + (rs & 63))) * 512 + colA; }
;                         else { const int sq = (row & 16383) - 15872; dst = out + (pn < 4 ? O_AKP : O_AVP) + (size_t)l * 2 * 512 * 512 + ((size_t)((row >> 14) * 512 + sq)) * 512 + colA; }
;                         *(f32x4*)dst = (f32x4){v[0], v[1], v[2], v[3]}; *(f32x4*)(dst + 4) = (f32x4){v[4], v[5], v[6], v[7]};
;                     }
;                     if (wrB && (samp || ai == 1)) {
;                         const int colB = c0 - (bj == 0 ? 2048 : 2176);
;                         float* dst;
;                         if (samp) { const int rs = row - MP; dst = out + (bj == 0 ? O_BKS : O_BVS) + (size_t)l * 16 * 128 * 128 + ((size_t)((rs >> 6) * 128 + 64 + (rs & 63))) * 128 + colB; }
;                         else { const int sq = (row & 16383) - 16256; dst = out + (bj == 0 ? O_BKP : O_BVP) + (size_t)l * 2 * 128 * 128 + ((size_t)((row >> 14) * 128 + sq)) * 128 + colB; }
;                         *(f32x4*)dst = (f32x4){v[0], v[1], v[2], v[3]}; *(f32x4*)(dst + 4) = (f32x4){v[4], v[5], v[6], v[7]};
;                     }
.LBB0_998:
	s_and_b64 vcc, exec, s[10:11]
	s_waitcnt lgkmcnt(3)
	v_cvt_pk_bf16_f32 v40, v36, v37
	s_waitcnt lgkmcnt(2)
	v_cvt_pk_bf16_f32 v41, v38, v39
	v_cvt_pk_bf16_f32 v42, v32, v33
	v_cvt_pk_bf16_f32 v43, v34, v35
	global_store_dwordx4 v[56:57], v[40:43], off offset:256 sc1
	s_cbranch_vccnz .LBB0_1000
	s_and_b64 s[30:31], s[6:7], exec
	s_cselect_b32 s36, s68, 0x200000
	v_lshl_add_u64 v[40:41], v[52:53], 0, s[36:37]
	v_lshl_add_u64 v[40:41], v[120:121], 2, v[40:41]
	global_store_dwordx4 v[40:41], v[36:39], off sc1
	global_store_dwordx4 v[40:41], v[32:35], off offset:16 sc1
.LBB0_1000:
	s_and_b64 vcc, exec, s[16:17]
	s_cbranch_vccnz .LBB0_1002
	s_and_b64 s[30:31], s[6:7], exec
	s_cselect_b32 s30, s0, 0x8c40000
	s_add_u32 s36, s58, s30
	s_addc_u32 s60, s59, 0
	s_and_b64 s[30:31], s[6:7], exec
	s_cselect_b32 s30, s71, 0x20000
	s_add_u32 s30, s36, s30
	s_addc_u32 s31, s60, 0
	v_lshl_add_u64 v[40:41], s[30:31], 0, v[54:55]
	v_lshl_add_u64 v[40:41], v[144:145], 2, v[40:41]
	global_store_dwordx4 v[40:41], v[36:39], off sc1
	global_store_dwordx4 v[40:41], v[32:35], off offset:16 sc1

;     __device__ __forceinline__ void operator()(AccRef acc, const pg8::Unit& u, int wr, int wc, int, int) const {
;     ...
;                 const int row = pm * 256 + ai * 128 + wr * 64 + m * 16 + fr;
;                 const float rstd = __builtin_amdgcn_rsqf(sq[ai][m] * (1.0f / DM) + EPS) * (isq ? QSCALE : 1.0f);
;                 const int pos = samp ? 2048 + ((row - MP) & 63) : (row & 16383);
; #pragma unroll
;                 for (int bj = 0; bj < 2; ++bj) {
;                     const int c0 = pn * 256 + bj * 128 + wc * 32 + 8 * fq;
;                     float v[8];
; #pragma unroll
;                     for (int j = 0; j < 4; ++j) { v[j] = acc[ai][bj][m][0][j] * rstd; v[4 + j] = acc[ai][bj][m][1][j] * rstd; }
;                     const bool ropet = (pn == 6 || pn == 7 || (pn == 8 && bj == 0)) && ((wc & 1) == 0);
;                     if (ropet) {
;                         float pv[8];
; #pragma unroll
;                         for (int j = 0; j < 8; ++j) pv[j] = __shfl_xor(v[j], 16);
;                         if (fq < 2) {
;                             const f32x4* cs = (const f32x4*)(rope + (size_t)pos * 16);
;                             const float sg = (fq == 0) ? -1.f : 1.f;
; #pragma unroll
;                             for (int jj = 0; jj < 4; ++jj) { const f32x4 t = cs[jj];
;                                 v[2 * jj] = v[2 * jj] * t[0] + sg * pv[2 * jj] * t[1];
;                                 v[2 * jj + 1] = v[2 * jj + 1] * t[2] + sg * pv[2 * jj + 1] * t[3]; }
;                         }
;                     }
;                     v4u w; w.x = cvt_pk(v[0], v[1]); w.y = cvt_pk(v[2], v[3]); w.z = cvt_pk(v[4], v[5]); w.w = cvt_pk(v[6], v[7]);
;                     *(v4u*)(Z + (size_t)row * NIN + c0) = w;
;                     if (wrA) {
;                         const int colA = c0 - (pn < 4 ? 512 : 1024);
;                         float* dst;
;                         if (samp) { const int rs = row - MP; dst = out + (pn < 4 ? O_AKS : O_AVS) + (size_t)l * 16 * 512 * 512 + ((size_t)((rs >> 6) * 512 + 448 + (rs & 63))) * 512 + colA; }
;                         else { const int sq = (row & 16383) - 15872; dst = out + (pn < 4 ? O_AKP : O_AVP) + (size_t)l * 2 * 512 * 512 + ((size_t)((row >> 14) * 512 + sq)) * 512 + colA; }
;                         *(f32x4*)dst = (f32x4){v[0], v[1], v[2], v[3]}; *(f32x4*)(dst + 4) = (f32x4){v[4], v[5], v[6], v[7]};
.LBB0_1006:
	s_waitcnt lgkmcnt(5)
	v_or_b32_e32 v38, 32, v74
	s_waitcnt lgkmcnt(2)
	v_mov_b64_e32 v[36:37], s[78:79]
	v_mad_i64_i32 v[40:41], s[30:31], v38, s63, v[36:37]
	v_add_u32_e32 v36, s3, v35
	v_ashrrev_i32_e32 v37, 31, v36
	v_lshlrev_b64 v[36:37], 11, v[36:37]
	s_waitcnt lgkmcnt(0)
	v_lshl_add_u64 v[42:43], s[82:83], 0, v[36:37]
	v_or_b32_e32 v36, s2, v106
	v_ashrrev_i32_e32 v37, 31, v36
	v_lshlrev_b64 v[36:37], 11, v[36:37]
	v_lshl_add_u64 v[44:45], s[80:81], 0, v[36:37]
	v_cvt_pk_bf16_f32 v36, v28, v29
	v_cvt_pk_bf16_f32 v37, v30, v31
	v_lshl_add_u64 v[40:41], v[146:147], 1, v[40:41]
	v_cvt_pk_bf16_f32 v38, v24, v25
	v_cvt_pk_bf16_f32 v39, v26, v27
	global_store_dwordx4 v[40:41], v[36:39], off sc1
	s_and_b64 vcc, exec, s[10:11]
	s_nop 0
	v_cndmask_b32_e64 v37, v43, v45, s[6:7]
	v_cndmask_b32_e64 v36, v42, v44, s[6:7]
	s_cbranch_vccnz .LBB0_1008
	s_and_b64 s[30:31], s[6:7], exec
	s_cselect_b32 s36, s68, 0x200000
	v_lshl_add_u64 v[38:39], v[36:37], 0, s[36:37]
	v_lshl_add_u64 v[38:39], v[148:149], 2, v[38:39]
	global_store_dwordx4 v[38:39], v[28:31], off sc1
	global_store_dwordx4 v[38:39], v[24:27], off offset:16 sc1
.LBB0_1008:
	v_add_u32_e32 v38, s51, v35
	v_or_b32_e32 v42, s49, v106
	v_ashrrev_i32_e32 v39, 31, v38
	v_ashrrev_i32_e32 v43, 31, v42
	v_lshlrev_b64 v[38:39], 9, v[38:39]
	v_lshlrev_b64 v[42:43], 9, v[42:43]
	s_and_b64 vcc, exec, s[16:17]
	v_cndmask_b32_e64 v39, v39, v43, s[6:7]
	v_cndmask_b32_e64 v38, v38, v42, s[6:7]
	s_cbranch_vccnz .LBB0_1010
	s_and_b64 s[30:31], s[6:7], exec
	s_cselect_b32 s30, s70, 0x8c00000
	s_add_u32 s36, s58, s30
	s_addc_u32 s60, s59, 0
	s_and_b64 s[30:31], s[6:7], exec
	s_cselect_b32 s30, s71, 0x20000
	s_add_u32 s30, s36, s30
	s_addc_u32 s31, s60, 0
	v_lshl_add_u64 v[42:43], s[30:31], 0, v[38:39]
	v_lshl_add_u64 v[42:43], v[144:145], 2, v[42:43]
	global_store_dwordx4 v[42:43], v[28:31], off sc1
	global_store_dwordx4 v[42:43], v[24:27], off offset:16 sc1

; __device__ __forceinline__ unsigned cvt_pk(float lo, float hi) { unsigned r; asm("v_cvt_pk_bf16_f32 %0, %1, %2" : "=v"(r) : "v"(lo), "v"(hi)); return r; }
;     __device__ __forceinline__ void operator()(AccRef acc, const pg8::Unit& u, int wr, int wc, int, int) const {
;     ...
;                     v4u w; w.x = cvt_pk(v[0], v[1]); w.y = cvt_pk(v[2], v[3]); w.z = cvt_pk(v[4], v[5]); w.w = cvt_pk(v[6], v[7]);
;                     *(v4u*)(Z + (size_t)row * NIN + c0) = w;
;                     if (wrA) {
;                         const int colA = c0 - (pn < 4 ? 512 : 1024);
;                         float* dst;
;                         if (samp) { const int rs = row - MP; dst = out + (pn < 4 ? O_AKS : O_AVS) + (size_t)l * 16 * 512 * 512 + ((size_t)((rs >> 6) * 512 + 448 + (rs & 63))) * 512 + colA; }
;                         else { const int sq = (row & 16383) - 15872; dst = out + (pn < 4 ? O_AKP : O_AVP) + (size_t)l * 2 * 512 * 512 + ((size_t)((row >> 14) * 512 + sq)) * 512 + colA; }
;                         *(f32x4*)dst = (f32x4){v[0], v[1], v[2], v[3]}; *(f32x4*)(dst + 4) = (f32x4){v[4], v[5], v[6], v[7]};
;                     }
;                     if (wrB && (samp || ai == 1)) {
;                         const int colB = c0 - (bj == 0 ? 2048 : 2176);
;                         float* dst;
;                         if (samp) { const int rs = row - MP; dst = out + (bj == 0 ? O_BKS : O_BVS) + (size_t)l * 16 * 128 * 128 + ((size_t)((rs >> 6) * 128 + 64 + (rs & 63))) * 128 + colB; }
;                         else { const int sq = (row & 16383) - 16256; dst = out + (bj == 0 ? O_BKP : O_BVP) + (size_t)l * 2 * 128 * 128 + ((size_t)((row >> 14) * 128 + sq)) * 128 + colB; }
;                         *(f32x4*)dst = (f32x4){v[0], v[1], v[2], v[3]}; *(f32x4*)(dst + 4) = (f32x4){v[4], v[5], v[6], v[7]};
.LBB0_1014:
	s_and_b64 vcc, exec, s[10:11]
	s_waitcnt lgkmcnt(3)
	v_cvt_pk_bf16_f32 v24, v20, v21
	s_waitcnt lgkmcnt(2)
	v_cvt_pk_bf16_f32 v25, v22, v23
	v_cvt_pk_bf16_f32 v26, v16, v17
	v_cvt_pk_bf16_f32 v27, v18, v19
	global_store_dwordx4 v[40:41], v[24:27], off offset:256 sc1
	s_cbranch_vccnz .LBB0_1016
	s_and_b64 s[30:31], s[6:7], exec
	s_cselect_b32 s36, s68, 0x200000
	v_lshl_add_u64 v[24:25], v[36:37], 0, s[36:37]
	v_lshl_add_u64 v[24:25], v[120:121], 2, v[24:25]
	global_store_dwordx4 v[24:25], v[20:23], off sc1
	global_store_dwordx4 v[24:25], v[16:19], off offset:16 sc1
.LBB0_1016:
	s_and_b64 vcc, exec, s[16:17]
	s_cbranch_vccnz .LBB0_1018
	s_and_b64 s[30:31], s[6:7], exec
	s_cselect_b32 s30, s0, 0x8c40000
	s_add_u32 s36, s58, s30
	s_addc_u32 s60, s59, 0
	s_and_b64 s[30:31], s[6:7], exec
	s_cselect_b32 s30, s71, 0x20000
	s_add_u32 s30, s36, s30
	s_addc_u32 s31, s60, 0
	v_lshl_add_u64 v[24:25], s[30:31], 0, v[38:39]
	v_lshl_add_u64 v[24:25], v[144:145], 2, v[24:25]
	global_store_dwordx4 v[24:25], v[20:23], off sc1
	global_store_dwordx4 v[24:25], v[16:19], off offset:16 sc1

; __device__ __forceinline__ unsigned cvt_pk(float lo, float hi) { unsigned r; asm("v_cvt_pk_bf16_f32 %0, %1, %2" : "=v"(r) : "v"(lo), "v"(hi)); return r; }
;     __device__ __forceinline__ void operator()(AccRef acc, const pg8::Unit& u, int wr, int wc, int, int) const {
;     ...
;                     v4u w; w.x = cvt_pk(v[0], v[1]); w.y = cvt_pk(v[2], v[3]); w.z = cvt_pk(v[4], v[5]); w.w = cvt_pk(v[6], v[7]);
;                     *(v4u*)(Z + (size_t)row * NIN + c0) = w;
;                     if (wrA) {
;                         const int colA = c0 - (pn < 4 ? 512 : 1024);
;                         float* dst;
;                         if (samp) { const int rs = row - MP; dst = out + (pn < 4 ? O_AKS : O_AVS) + (size_t)l * 16 * 512 * 512 + ((size_t)((rs >> 6) * 512 + 448 + (rs & 63))) * 512 + colA; }
;                         else { const int sq = (row & 16383) - 15872; dst = out + (pn < 4 ? O_AKP : O_AVP) + (size_t)l * 2 * 512 * 512 + ((size_t)((row >> 14) * 512 + sq)) * 512 + colA; }
;                         *(f32x4*)dst = (f32x4){v[0], v[1], v[2], v[3]}; *(f32x4*)(dst + 4) = (f32x4){v[4], v[5], v[6], v[7]};
;                     }
;                     if (wrB && (samp || ai == 1)) {
;                         const int colB = c0 - (bj == 0 ? 2048 : 2176);
;                         float* dst;
;                         if (samp) { const int rs = row - MP; dst = out + (bj == 0 ? O_BKS : O_BVS) + (size_t)l * 16 * 128 * 128 + ((size_t)((rs >> 6) * 128 + 64 + (rs & 63))) * 128 + colB; }
;                         else { const int sq = (row & 16383) - 16256; dst = out + (bj == 0 ? O_BKP : O_BVP) + (size_t)l * 2 * 128 * 128 + ((size_t)((row >> 14) * 128 + sq)) * 128 + colB; }
;                         *(f32x4*)dst = (f32x4){v[0], v[1], v[2], v[3]}; *(f32x4*)(dst + 4) = (f32x4){v[4], v[5], v[6], v[7]};
.LBB0_1022:
	s_waitcnt lgkmcnt(5)
	v_or_b32_e32 v22, 48, v74
	s_waitcnt lgkmcnt(2)
	v_mov_b64_e32 v[20:21], s[78:79]
	v_mad_i64_i32 v[24:25], s[12:13], v22, s63, v[20:21]
	v_add_u32_e32 v20, s3, v19
	v_ashrrev_i32_e32 v21, 31, v20
	v_lshlrev_b64 v[20:21], 11, v[20:21]
	s_waitcnt lgkmcnt(0)
	v_lshl_add_u64 v[26:27], s[82:83], 0, v[20:21]
	v_or_b32_e32 v20, s2, v90
	v_ashrrev_i32_e32 v21, 31, v20
	v_lshlrev_b64 v[20:21], 11, v[20:21]
	v_lshl_add_u64 v[28:29], s[80:81], 0, v[20:21]
	v_cvt_pk_bf16_f32 v20, v12, v13
	v_cvt_pk_bf16_f32 v21, v14, v15
	v_lshl_add_u64 v[24:25], v[146:147], 1, v[24:25]
	v_cvt_pk_bf16_f32 v22, v8, v9
	v_cvt_pk_bf16_f32 v23, v10, v11
	global_store_dwordx4 v[24:25], v[20:23], off sc1
	s_and_b64 vcc, exec, s[10:11]
	s_nop 0
	v_cndmask_b32_e64 v21, v27, v29, s[6:7]
	v_cndmask_b32_e64 v20, v26, v28, s[6:7]
	s_cbranch_vccnz .LBB0_1024
	s_and_b64 s[2:3], s[6:7], exec
	s_cselect_b32 s36, s68, 0x200000
	v_lshl_add_u64 v[22:23], v[20:21], 0, s[36:37]
	v_lshl_add_u64 v[22:23], v[148:149], 2, v[22:23]
	global_store_dwordx4 v[22:23], v[12:15], off sc1
	global_store_dwordx4 v[22:23], v[8:11], off offset:16 sc1
.LBB0_1024:
	v_add_u32_e32 v22, s51, v19
	v_or_b32_e32 v26, s49, v90
	v_ashrrev_i32_e32 v23, 31, v22
	v_ashrrev_i32_e32 v27, 31, v26
	v_lshlrev_b64 v[22:23], 9, v[22:23]
	v_lshlrev_b64 v[26:27], 9, v[26:27]
	s_and_b64 vcc, exec, s[16:17]
	v_cndmask_b32_e64 v23, v23, v27, s[6:7]
	v_cndmask_b32_e64 v22, v22, v26, s[6:7]
	s_cbranch_vccnz .LBB0_1026
	s_and_b64 s[2:3], s[6:7], exec
	s_cselect_b32 s2, s70, 0x8c00000
	s_add_u32 s12, s58, s2
	s_addc_u32 s13, s59, 0
	s_and_b64 s[2:3], s[6:7], exec
	s_cselect_b32 s2, s71, 0x20000
	s_add_u32 s2, s12, s2
	s_addc_u32 s3, s13, 0
	v_lshl_add_u64 v[26:27], s[2:3], 0, v[22:23]
	v_lshl_add_u64 v[26:27], v[144:145], 2, v[26:27]
	global_store_dwordx4 v[26:27], v[12:15], off sc1
	global_store_dwordx4 v[26:27], v[8:11], off offset:16 sc1

; __device__ __forceinline__ unsigned cvt_pk(float lo, float hi) { unsigned r; asm("v_cvt_pk_bf16_f32 %0, %1, %2" : "=v"(r) : "v"(lo), "v"(hi)); return r; }
;     __device__ __forceinline__ void operator()(AccRef acc, const pg8::Unit& u, int wr, int wc, int, int) const {
;     ...
;                     v4u w; w.x = cvt_pk(v[0], v[1]); w.y = cvt_pk(v[2], v[3]); w.z = cvt_pk(v[4], v[5]); w.w = cvt_pk(v[6], v[7]);
;                     *(v4u*)(Z + (size_t)row * NIN + c0) = w;
;                     if (wrA) {
;                         const int colA = c0 - (pn < 4 ? 512 : 1024);
;                         float* dst;
;                         if (samp) { const int rs = row - MP; dst = out + (pn < 4 ? O_AKS : O_AVS) + (size_t)l * 16 * 512 * 512 + ((size_t)((rs >> 6) * 512 + 448 + (rs & 63))) * 512 + colA; }
;                         else { const int sq = (row & 16383) - 15872; dst = out + (pn < 4 ? O_AKP : O_AVP) + (size_t)l * 2 * 512 * 512 + ((size_t)((row >> 14) * 512 + sq)) * 512 + colA; }
;                         *(f32x4*)dst = (f32x4){v[0], v[1], v[2], v[3]}; *(f32x4*)(dst + 4) = (f32x4){v[4], v[5], v[6], v[7]};
;                     }
;                     if (wrB && (samp || ai == 1)) {
.LBB0_1030:
	s_and_b64 vcc, exec, s[10:11]
	s_waitcnt lgkmcnt(3)
	v_cvt_pk_bf16_f32 v8, v4, v5
	s_waitcnt lgkmcnt(2)
	v_cvt_pk_bf16_f32 v9, v6, v7
	v_cvt_pk_bf16_f32 v10, v0, v1
	v_cvt_pk_bf16_f32 v11, v2, v3
	global_store_dwordx4 v[24:25], v[8:11], off offset:256 sc1
	s_cbranch_vccz .LBB0_1033
	s_and_b64 vcc, exec, s[16:17]
	s_cbranch_vccz .LBB0_1034

;     __device__ __forceinline__ void operator()(AccRef acc, const pg8::Unit& u, int wr, int wc, int, int) const {
;     ...
;                     if (wrA) {
;                         const int colA = c0 - (pn < 4 ? 512 : 1024);
;                         float* dst;
;                         if (samp) { const int rs = row - MP; dst = out + (pn < 4 ? O_AKS : O_AVS) + (size_t)l * 16 * 512 * 512 + ((size_t)((rs >> 6) * 512 + 448 + (rs & 63))) * 512 + colA; }
;                         else { const int sq = (row & 16383) - 15872; dst = out + (pn < 4 ? O_AKP : O_AVP) + (size_t)l * 2 * 512 * 512 + ((size_t)((row >> 14) * 512 + sq)) * 512 + colA; }
;                         *(f32x4*)dst = (f32x4){v[0], v[1], v[2], v[3]}; *(f32x4*)(dst + 4) = (f32x4){v[4], v[5], v[6], v[7]};
;                     }
;                     if (wrB && (samp || ai == 1)) {
;                         const int colB = c0 - (bj == 0 ? 2048 : 2176);
;                         float* dst;
;                         if (samp) { const int rs = row - MP; dst = out + (bj == 0 ? O_BKS : O_BVS) + (size_t)l * 16 * 128 * 128 + ((size_t)((rs >> 6) * 128 + 64 + (rs & 63))) * 128 + colB; }
;                         else { const int sq = (row & 16383) - 16256; dst = out + (bj == 0 ? O_BKP : O_BVP) + (size_t)l * 2 * 128 * 128 + ((size_t)((row >> 14) * 128 + sq)) * 128 + colB; }
;                         *(f32x4*)dst = (f32x4){v[0], v[1], v[2], v[3]}; *(f32x4*)(dst + 4) = (f32x4){v[4], v[5], v[6], v[7]};
.LBB0_1033:
	s_and_b64 s[2:3], s[6:7], exec
	s_cselect_b32 s36, s68, 0x200000
	v_lshl_add_u64 v[8:9], v[20:21], 0, s[36:37]
	v_lshl_add_u64 v[8:9], v[120:121], 2, v[8:9]
	global_store_dwordx4 v[8:9], v[4:7], off sc1
	global_store_dwordx4 v[8:9], v[0:3], off offset:16 sc1
	s_and_b64 vcc, exec, s[16:17]
	s_cbranch_vccnz .LBB0_1032
.LBB0_1034:
	s_and_b64 s[2:3], s[6:7], exec
	s_cselect_b32 s2, s0, 0x8c40000
	s_add_u32 s8, s58, s2
	s_addc_u32 s9, s59, 0
	s_and_b64 s[2:3], s[6:7], exec
	s_cselect_b32 s2, s71, 0x20000
	s_add_u32 s2, s8, s2
	s_addc_u32 s3, s9, 0
	v_lshl_add_u64 v[8:9], s[2:3], 0, v[22:23]
	v_lshl_add_u64 v[8:9], v[144:145], 2, v[8:9]
	global_store_dwordx4 v[8:9], v[4:7], off sc1
	global_store_dwordx4 v[8:9], v[0:3], off offset:16 sc1
	s_andn2_b64 vcc, exec, s[52:53]
	s_mov_b64 s[6:7], -1
	s_cbranch_vccnz .LBB0_896
